# GEMM k-loops: issue the two B-tile global loads after the four LDS fragment reads of each half-iteration (was before); counted waits unchanged
# baseline (speedup 1.0000x reference)
.LBB0_216:
	s_add_i32 s3, s1, 4
	s_min_u32 s4, s3, 31
	s_lshl_b32 s96, s4, 13
	v_lshl_add_u64 v[168:169], v[186:187], 0, s[96:97]
	v_add_co_u32_e32 v172, vcc, s85, v168
	s_add_i32 s3, s1, 2
	s_nop 0
	v_addc_co_u32_e32 v173, vcc, 0, v169, vcc
	ds_read_b128 v[236:239], v235
	ds_read_b128 v[240:243], v235 offset:2560
	ds_read_b128 v[244:247], v235 offset:5120
	ds_read_b128 v[248:251], v235 offset:7680
	global_load_dwordx4 v[168:171], v[168:169], off
	s_nop 0
	global_load_dwordx4 v[172:175], v[172:173], off
	s_lshl_b32 s96, s4, 11
	s_waitcnt vmcnt(10) lgkmcnt(3)
	v_mfma_f32_32x32x16_bf16 v[16:31], v[160:163], v[236:239], v[16:31]
	s_min_u32 s1, s3, 28
	s_add_i32 s1, s1, 3
	s_waitcnt lgkmcnt(2)
	v_mfma_f32_32x32x16_bf16 v[112:127], v[160:163], v[240:243], v[112:127]
	s_waitcnt vmcnt(7)
	v_mfma_f32_32x32x16_bf16 v[0:15], v[164:167], v[236:239], v[0:15]
	ds_read_b128 v[236:239], v235 offset:5152
	s_waitcnt lgkmcnt(2)
	v_mfma_f32_32x32x16_bf16 v[80:95], v[160:163], v[244:247], v[80:95]
	v_mfma_f32_32x32x16_bf16 v[96:111], v[164:167], v[240:243], v[96:111]
	ds_read_b128 v[240:243], v235 offset:7712
	s_waitcnt lgkmcnt(2)
	v_mfma_f32_32x32x16_bf16 v[64:79], v[160:163], v[248:251], v[64:79]
	ds_read_b128 v[160:163], v235 offset:32
	v_mfma_f32_32x32x16_bf16 v[48:63], v[164:167], v[244:247], v[48:63]
	v_mfma_f32_32x32x16_bf16 v[32:47], v[164:167], v[248:251], v[32:47]
	ds_read_b128 v[164:167], v235 offset:2592
	s_waitcnt vmcnt(3)
	ds_write_b128 v188, v[140:143] offset:10240
	s_waitcnt vmcnt(2)
	ds_write_b128 v188, v[144:147] offset:15360
	v_lshl_add_u64 v[140:141], v[184:185], 0, s[96:97]
	v_add_co_u32_e32 v142, vcc, s41, v140
	s_lshl_b32 s96, s1, 13
	s_nop 0
	v_addc_co_u32_e32 v143, vcc, 0, v141, vcc
	v_lshl_add_u64 v[144:145], v[186:187], 0, s[96:97]
	v_add_co_u32_e32 v146, vcc, s85, v144
	s_waitcnt lgkmcnt(3)
	v_mfma_f32_32x32x16_bf16 v[16:31], v[148:151], v[160:163], v[16:31]
	v_addc_co_u32_e32 v147, vcc, 0, v145, vcc
	s_waitcnt lgkmcnt(2)
	v_mfma_f32_32x32x16_bf16 v[112:127], v[148:151], v[164:167], v[112:127]
	v_mfma_f32_32x32x16_bf16 v[80:95], v[148:151], v[236:239], v[80:95]
	v_mfma_f32_32x32x16_bf16 v[64:79], v[148:151], v[240:243], v[64:79]
	v_mfma_f32_32x32x16_bf16 v[0:15], v[128:131], v[160:163], v[0:15]
	v_mfma_f32_32x32x16_bf16 v[96:111], v[128:131], v[164:167], v[96:111]
	global_load_dwordx4 v[164:167], v[142:143], off
	global_load_dwordx4 v[160:163], v[140:141], off
	global_load_dwordx4 v[148:151], v[140:141], off offset:1024
	v_mfma_f32_32x32x16_bf16 v[48:63], v[128:131], v[236:239], v[48:63]
	v_mfma_f32_32x32x16_bf16 v[32:47], v[128:131], v[240:243], v[32:47]
	global_load_dwordx4 v[128:131], v[142:143], off offset:1024
	s_waitcnt lgkmcnt(0)
	s_barrier
	ds_read_b128 v[236:239], v235 offset:10240
	ds_read_b128 v[240:243], v235 offset:12800
	ds_read_b128 v[244:247], v235 offset:15360
	ds_read_b128 v[248:251], v235 offset:17920
	global_load_dwordx4 v[140:143], v[144:145], off
	s_nop 0
	global_load_dwordx4 v[144:147], v[146:147], off
	s_lshl_b32 s96, s1, 11
	s_waitcnt lgkmcnt(3)
	v_mfma_f32_32x32x16_bf16 v[16:31], v[152:155], v[236:239], v[16:31]
	s_mov_b32 s1, s3
	s_cmp_gt_u32 s3, 29
	s_waitcnt lgkmcnt(2)
	v_mfma_f32_32x32x16_bf16 v[112:127], v[152:155], v[240:243], v[112:127]
	v_mfma_f32_32x32x16_bf16 v[0:15], v[156:159], v[236:239], v[0:15]
	ds_read_b128 v[236:239], v235 offset:15392
	s_waitcnt lgkmcnt(2)
	v_mfma_f32_32x32x16_bf16 v[80:95], v[152:155], v[244:247], v[80:95]
	v_mfma_f32_32x32x16_bf16 v[96:111], v[156:159], v[240:243], v[96:111]
	ds_read_b128 v[240:243], v235 offset:17952
	s_waitcnt lgkmcnt(2)
	v_mfma_f32_32x32x16_bf16 v[64:79], v[152:155], v[248:251], v[64:79]
	ds_read_b128 v[152:155], v235 offset:10272
	v_mfma_f32_32x32x16_bf16 v[48:63], v[156:159], v[244:247], v[48:63]
	v_mfma_f32_32x32x16_bf16 v[32:47], v[156:159], v[248:251], v[32:47]
	ds_read_b128 v[156:159], v235 offset:12832
	s_waitcnt lgkmcnt(1)
	v_mfma_f32_32x32x16_bf16 v[16:31], v[136:139], v[152:155], v[16:31]
	s_waitcnt lgkmcnt(0)
	v_mfma_f32_32x32x16_bf16 v[112:127], v[136:139], v[156:159], v[112:127]
	v_mfma_f32_32x32x16_bf16 v[80:95], v[136:139], v[236:239], v[80:95]
	v_mfma_f32_32x32x16_bf16 v[64:79], v[136:139], v[240:243], v[64:79]
	v_lshl_add_u64 v[136:137], v[184:185], 0, s[96:97]
	v_add_co_u32_e32 v196, vcc, s41, v136
	s_nop 1
	v_addc_co_u32_e32 v197, vcc, 0, v137, vcc
	v_mfma_f32_32x32x16_bf16 v[0:15], v[132:135], v[152:155], v[0:15]
	v_mfma_f32_32x32x16_bf16 v[96:111], v[132:135], v[156:159], v[96:111]
	global_load_dwordx4 v[156:159], v[196:197], off
	global_load_dwordx4 v[152:155], v[136:137], off
	s_nop 0
	global_load_dwordx4 v[136:139], v[136:137], off offset:1024
	v_mfma_f32_32x32x16_bf16 v[48:63], v[132:135], v[236:239], v[48:63]
	v_mfma_f32_32x32x16_bf16 v[32:47], v[132:135], v[240:243], v[32:47]
	global_load_dwordx4 v[132:135], v[196:197], off offset:1024
	s_waitcnt vmcnt(11)
	ds_write_b128 v188, v[168:171]
	s_waitcnt vmcnt(10)
	ds_write_b128 v188, v[172:175] offset:5120
	s_waitcnt lgkmcnt(0)
	s_barrier
	s_cbranch_scc0 .LBB0_216
	s_lshl_b32 s12, s2, 8
	s_cmp_eq_u32 s0, 23
	s_mov_b64 s[2:3], -1
	s_cbranch_scc1 .LBB0_347
	s_movk_i32 s1, 0x2400
	s_waitcnt vmcnt(6)
	v_and_b32_e32 v130, 0xffffffc0, v181
	s_cmp_gt_i32 s0, 10
	v_mul_lo_u32 v129, v233, s1
	v_and_b32_e32 v128, 56, v234
	v_add_u32_e32 v131, s12, v130
	s_cselect_b64 s[2:3], -1, 0
	s_cmp_gt_u32 s0, 19
	v_mul_u32_u24_e32 v130, 0x120, v183
	s_waitcnt vmcnt(0)
	v_lshl_or_b32 v132, v128, 1, v129
	v_lshl_or_b32 v128, s0, 7, v128
	s_cselect_b64 s[0:1], -1, 0
	v_lshl_add_u32 v129, v130, 1, v129
	v_lshl_or_b32 v130, v231, 1, v129
	v_cvt_pk_bf16_f32 v112, v112, s0
	ds_write_b16 v130, v112 offset:64
	v_cvt_pk_bf16_f32 v112, v17, s0
	v_cvt_pk_bf16_f32 v96, v96, s0
	ds_write_b16 v130, v112 offset:144
	v_cvt_pk_bf16_f32 v112, v113, s0
	ds_write_b16 v130, v96 offset:4672
	v_cvt_pk_bf16_f32 v96, v1, s0
	ds_write_b16 v130, v112 offset:208
	v_cvt_pk_bf16_f32 v112, v18, s0
	ds_write_b16 v130, v96 offset:4752
	v_cvt_pk_bf16_f32 v96, v97, s0
	ds_write_b16 v130, v112 offset:288
	v_cvt_pk_bf16_f32 v112, v114, s0
	ds_write_b16 v130, v96 offset:4816
	v_cvt_pk_bf16_f32 v96, v2, s0
	ds_write_b16 v130, v112 offset:352
	v_cvt_pk_bf16_f32 v112, v19, s0
	ds_write_b16 v130, v96 offset:4896
	v_cvt_pk_bf16_f32 v96, v98, s0
	ds_write_b16 v130, v112 offset:432
	v_cvt_pk_bf16_f32 v112, v115, s0
	ds_write_b16 v130, v96 offset:4960
	v_cvt_pk_bf16_f32 v96, v3, s0
	ds_write_b16 v130, v112 offset:496
	v_cvt_pk_bf16_f32 v112, v20, s0
	ds_write_b16 v130, v96 offset:5040
	v_cvt_pk_bf16_f32 v96, v99, s0
	ds_write_b16 v130, v112 offset:1152
	v_cvt_pk_bf16_f32 v112, v116, s0
	ds_write_b16 v130, v96 offset:5104
	v_cvt_pk_bf16_f32 v96, v4, s0
	ds_write_b16 v130, v112 offset:1216
	v_cvt_pk_bf16_f32 v112, v21, s0
	ds_write_b16 v130, v96 offset:5760
	v_cvt_pk_bf16_f32 v96, v100, s0
	ds_write_b16 v130, v112 offset:1296
	v_cvt_pk_bf16_f32 v112, v117, s0
	ds_write_b16 v130, v96 offset:5824
	v_cvt_pk_bf16_f32 v96, v5, s0
	ds_write_b16 v130, v112 offset:1360
	v_cvt_pk_bf16_f32 v112, v22, s0
	ds_write_b16 v130, v96 offset:5904
	v_cvt_pk_bf16_f32 v96, v101, s0
	ds_write_b16 v130, v112 offset:1440
	v_cvt_pk_bf16_f32 v112, v118, s0
	ds_write_b16 v130, v96 offset:5968
	v_cvt_pk_bf16_f32 v96, v6, s0
	ds_write_b16 v130, v112 offset:1504
	v_cvt_pk_bf16_f32 v112, v23, s0
	ds_write_b16 v130, v96 offset:6048
	v_cvt_pk_bf16_f32 v96, v102, s0
	ds_write_b16 v130, v112 offset:1584
	v_cvt_pk_bf16_f32 v112, v119, s0
	ds_write_b16 v130, v96 offset:6112
	v_cvt_pk_bf16_f32 v96, v7, s0
	ds_write_b16 v130, v112 offset:1648
	v_cvt_pk_bf16_f32 v112, v24, s0
	ds_write_b16 v130, v96 offset:6192
	v_cvt_pk_bf16_f32 v96, v103, s0
	ds_write_b16 v130, v112 offset:2304
	v_cvt_pk_bf16_f32 v112, v120, s0
	ds_write_b16 v130, v96 offset:6256
	v_cvt_pk_bf16_f32 v96, v8, s0
	ds_write_b16 v130, v112 offset:2368
	v_cvt_pk_bf16_f32 v112, v25, s0
	ds_write_b16 v130, v96 offset:6912
	v_cvt_pk_bf16_f32 v96, v104, s0
	ds_write_b16 v130, v112 offset:2448
	v_cvt_pk_bf16_f32 v112, v121, s0
	ds_write_b16 v130, v96 offset:6976
	v_cvt_pk_bf16_f32 v96, v9, s0
	ds_write_b16 v130, v112 offset:2512
	v_cvt_pk_bf16_f32 v112, v26, s0
	ds_write_b16 v130, v96 offset:7056
	v_cvt_pk_bf16_f32 v96, v105, s0
	ds_write_b16 v130, v112 offset:2592
	v_cvt_pk_bf16_f32 v112, v122, s0
	ds_write_b16 v130, v96 offset:7120
	v_cvt_pk_bf16_f32 v96, v10, s0
	ds_write_b16 v130, v112 offset:2656
	v_cvt_pk_bf16_f32 v112, v27, s0
	ds_write_b16 v130, v96 offset:7200
	v_cvt_pk_bf16_f32 v96, v106, s0
	ds_write_b16 v130, v112 offset:2736
	v_cvt_pk_bf16_f32 v112, v123, s0
	ds_write_b16 v130, v96 offset:7264
	v_cvt_pk_bf16_f32 v96, v11, s0
	ds_write_b16 v130, v112 offset:2800
	v_cvt_pk_bf16_f32 v112, v28, s0
	ds_write_b16 v130, v96 offset:7344
	v_cvt_pk_bf16_f32 v96, v107, s0
	ds_write_b16 v130, v112 offset:3456
	v_cvt_pk_bf16_f32 v112, v124, s0
	ds_write_b16 v130, v96 offset:7408
	v_cvt_pk_bf16_f32 v96, v12, s0
	ds_write_b16 v130, v112 offset:3520
	v_cvt_pk_bf16_f32 v112, v29, s0
	ds_write_b16 v130, v96 offset:8064
	v_cvt_pk_bf16_f32 v96, v108, s0
	ds_write_b16 v130, v112 offset:3600
	v_cvt_pk_bf16_f32 v112, v125, s0
	ds_write_b16 v130, v96 offset:8128
	v_cvt_pk_bf16_f32 v96, v13, s0
	ds_write_b16 v130, v112 offset:3664
	v_cvt_pk_bf16_f32 v112, v30, s0
	ds_write_b16 v130, v96 offset:8208
	v_cvt_pk_bf16_f32 v96, v109, s0
	ds_write_b16 v130, v112 offset:3744
	v_cvt_pk_bf16_f32 v112, v126, s0
	ds_write_b16 v130, v96 offset:8272
	v_cvt_pk_bf16_f32 v96, v14, s0
	ds_write_b16 v130, v112 offset:3808
	v_cvt_pk_bf16_f32 v112, v31, s0
	ds_write_b16 v130, v96 offset:8352
	v_cvt_pk_bf16_f32 v96, v110, s0
	ds_write_b16 v130, v112 offset:3888
	v_cvt_pk_bf16_f32 v112, v127, s0
	ds_write_b16 v130, v96 offset:8416
	v_cvt_pk_bf16_f32 v96, v15, s0
	v_cvt_pk_bf16_f32 v133, v16, s0
	ds_write_b16 v130, v112 offset:3952
	v_cvt_pk_bf16_f32 v112, v0, s0
	ds_write_b16 v130, v96 offset:8496
	v_cvt_pk_bf16_f32 v96, v111, s0
	ds_write_b16 v130, v133
	ds_write_b16 v130, v112 offset:4608
	ds_write_b16 v130, v96 offset:8560
	v_lshrrev_b32_e32 v109, 3, v232
	s_waitcnt lgkmcnt(0)
	v_mad_u32_u24 v96, v109, s42, v132
	ds_read_b128 v[96:99], v96
	v_mov_b32_e32 v176, v128
	v_or_b32_e32 v110, v131, v109
	s_mov_b64 s[4:5], -1
	s_and_b64 vcc, exec, s[2:3]
	s_cbranch_vccz .LBB0_224
	s_and_b64 vcc, exec, s[0:1]
	s_cbranch_vccz .LBB0_221
	v_readlane_b32 s16, v254, 15
	v_readlane_b32 s18, v254, 17
	v_readlane_b32 s19, v254, 18
	v_readlane_b32 s17, v254, 16
	v_readlane_b32 s20, v254, 19
	v_mov_b64_e32 v[100:101], s[18:19]
	v_mad_i64_i32 v[100:101], s[4:5], v110, s89, v[100:101]
	s_movk_i32 s4, 0xec00
	v_lshl_add_u64 v[100:101], v[176:177], 1, v[100:101]
	s_mov_b32 s5, -1
	v_readlane_b32 s21, v254, 20
	v_readlane_b32 s22, v254, 21
	v_readlane_b32 s23, v254, 22
	v_readlane_b32 s24, v254, 23
	v_readlane_b32 s25, v254, 24
	v_readlane_b32 s26, v254, 25
	v_readlane_b32 s27, v254, 26
	v_readlane_b32 s28, v254, 27
	v_readlane_b32 s29, v254, 28
	v_readlane_b32 s30, v254, 29
	v_readlane_b32 s31, v254, 30
	v_lshl_add_u64 v[100:101], v[100:101], 0, s[4:5]
	s_mov_b64 s[4:5], 0

.LBB0_924:
	s_add_i32 s9, s3, 4
	s_min_u32 s10, s9, 31
	s_lshl_b32 s96, s10, 13
	v_lshl_add_u64 v[168:169], v[186:187], 0, s[96:97]
	v_add_co_u32_e32 v172, vcc, s85, v168
	s_add_i32 s9, s3, 2
	s_nop 0
	v_addc_co_u32_e32 v173, vcc, 0, v169, vcc
	ds_read_b128 v[196:199], v240
	ds_read_b128 v[200:203], v240 offset:2560
	ds_read_b128 v[204:207], v240 offset:5120
	ds_read_b128 v[242:245], v240 offset:7680
	global_load_dwordx4 v[168:171], v[168:169], off
	s_nop 0
	global_load_dwordx4 v[172:175], v[172:173], off
	s_lshl_b32 s96, s10, 11
	s_waitcnt vmcnt(10) lgkmcnt(3)
	v_mfma_f32_32x32x16_bf16 v[112:127], v[160:163], v[196:199], v[112:127]
	s_min_u32 s3, s9, 28
	s_add_i32 s3, s3, 3
	s_waitcnt lgkmcnt(2)
	v_mfma_f32_32x32x16_bf16 v[96:111], v[160:163], v[200:203], v[96:111]
	s_waitcnt vmcnt(7)
	v_mfma_f32_32x32x16_bf16 v[48:63], v[164:167], v[196:199], v[48:63]
	ds_read_b128 v[196:199], v240 offset:5152
	s_waitcnt lgkmcnt(2)
	v_mfma_f32_32x32x16_bf16 v[80:95], v[160:163], v[204:207], v[80:95]
	v_mfma_f32_32x32x16_bf16 v[32:47], v[164:167], v[200:203], v[32:47]
	ds_read_b128 v[200:203], v240 offset:7712
	s_waitcnt lgkmcnt(2)
	v_mfma_f32_32x32x16_bf16 v[64:79], v[160:163], v[242:245], v[64:79]
	ds_read_b128 v[160:163], v240 offset:32
	v_mfma_f32_32x32x16_bf16 v[16:31], v[164:167], v[204:207], v[16:31]
	v_mfma_f32_32x32x16_bf16 v[0:15], v[164:167], v[242:245], v[0:15]
	ds_read_b128 v[164:167], v240 offset:2592
	s_waitcnt vmcnt(3)
	ds_write_b128 v188, v[140:143] offset:10240
	s_waitcnt vmcnt(2)
	ds_write_b128 v188, v[144:147] offset:15360
	v_lshl_add_u64 v[140:141], v[184:185], 0, s[96:97]
	v_add_co_u32_e32 v142, vcc, s41, v140
	s_lshl_b32 s96, s3, 13
	s_nop 0
	v_addc_co_u32_e32 v143, vcc, 0, v141, vcc
	v_lshl_add_u64 v[144:145], v[186:187], 0, s[96:97]
	v_add_co_u32_e32 v146, vcc, s85, v144
	s_waitcnt lgkmcnt(3)
	v_mfma_f32_32x32x16_bf16 v[112:127], v[148:151], v[160:163], v[112:127]
	v_addc_co_u32_e32 v147, vcc, 0, v145, vcc
	s_waitcnt lgkmcnt(2)
	v_mfma_f32_32x32x16_bf16 v[96:111], v[148:151], v[164:167], v[96:111]
	v_mfma_f32_32x32x16_bf16 v[80:95], v[148:151], v[196:199], v[80:95]
	v_mfma_f32_32x32x16_bf16 v[64:79], v[148:151], v[200:203], v[64:79]
	v_mfma_f32_32x32x16_bf16 v[48:63], v[128:131], v[160:163], v[48:63]
	v_mfma_f32_32x32x16_bf16 v[32:47], v[128:131], v[164:167], v[32:47]
	global_load_dwordx4 v[164:167], v[142:143], off
	global_load_dwordx4 v[160:163], v[140:141], off
	global_load_dwordx4 v[148:151], v[140:141], off offset:1024
	v_mfma_f32_32x32x16_bf16 v[16:31], v[128:131], v[196:199], v[16:31]
	v_mfma_f32_32x32x16_bf16 v[0:15], v[128:131], v[200:203], v[0:15]
	global_load_dwordx4 v[128:131], v[142:143], off offset:1024
	s_waitcnt lgkmcnt(0)
	s_barrier
	ds_read_b128 v[196:199], v240 offset:10240
	ds_read_b128 v[200:203], v240 offset:12800
	ds_read_b128 v[204:207], v240 offset:15360
	ds_read_b128 v[242:245], v240 offset:17920
	global_load_dwordx4 v[140:143], v[144:145], off
	s_nop 0
	global_load_dwordx4 v[144:147], v[146:147], off
	s_lshl_b32 s96, s3, 11
	s_waitcnt lgkmcnt(3)
	v_mfma_f32_32x32x16_bf16 v[112:127], v[152:155], v[196:199], v[112:127]
	s_mov_b32 s3, s9
	s_cmp_lt_u32 s9, 30
	s_waitcnt lgkmcnt(2)
	v_mfma_f32_32x32x16_bf16 v[96:111], v[152:155], v[200:203], v[96:111]
	v_mfma_f32_32x32x16_bf16 v[48:63], v[156:159], v[196:199], v[48:63]
	ds_read_b128 v[196:199], v240 offset:15392
	s_waitcnt lgkmcnt(2)
	v_mfma_f32_32x32x16_bf16 v[80:95], v[152:155], v[204:207], v[80:95]
	v_mfma_f32_32x32x16_bf16 v[32:47], v[156:159], v[200:203], v[32:47]
	ds_read_b128 v[200:203], v240 offset:17952
	s_waitcnt lgkmcnt(2)
	v_mfma_f32_32x32x16_bf16 v[64:79], v[152:155], v[242:245], v[64:79]
	ds_read_b128 v[152:155], v240 offset:10272
	v_mfma_f32_32x32x16_bf16 v[16:31], v[156:159], v[204:207], v[16:31]
	v_mfma_f32_32x32x16_bf16 v[0:15], v[156:159], v[242:245], v[0:15]
	ds_read_b128 v[156:159], v240 offset:12832
	s_waitcnt lgkmcnt(1)
	v_mfma_f32_32x32x16_bf16 v[112:127], v[136:139], v[152:155], v[112:127]
	s_waitcnt lgkmcnt(0)
	v_mfma_f32_32x32x16_bf16 v[96:111], v[136:139], v[156:159], v[96:111]
	v_mfma_f32_32x32x16_bf16 v[80:95], v[136:139], v[196:199], v[80:95]
	v_mfma_f32_32x32x16_bf16 v[64:79], v[136:139], v[200:203], v[64:79]
	v_lshl_add_u64 v[136:137], v[184:185], 0, s[96:97]
	v_mfma_f32_32x32x16_bf16 v[16:31], v[132:135], v[196:199], v[16:31]
	v_add_co_u32_e32 v196, vcc, s41, v136
	s_nop 1
	v_addc_co_u32_e32 v197, vcc, 0, v137, vcc
	v_mfma_f32_32x32x16_bf16 v[48:63], v[132:135], v[152:155], v[48:63]
	v_mfma_f32_32x32x16_bf16 v[32:47], v[132:135], v[156:159], v[32:47]
	global_load_dwordx4 v[156:159], v[196:197], off
	global_load_dwordx4 v[152:155], v[136:137], off
	s_nop 0
	global_load_dwordx4 v[136:139], v[136:137], off offset:1024
	v_mfma_f32_32x32x16_bf16 v[0:15], v[132:135], v[200:203], v[0:15]
	global_load_dwordx4 v[132:135], v[196:197], off offset:1024
	s_waitcnt vmcnt(11)
	ds_write_b128 v188, v[168:171]
	s_waitcnt vmcnt(10)
	ds_write_b128 v188, v[172:175] offset:5120
	s_waitcnt lgkmcnt(0)
	s_barrier
	s_cbranch_scc1 .LBB0_924
	s_movk_i32 s3, 0x2400
	s_waitcnt vmcnt(6)
	v_lshlrev_b32_e32 v128, 2, v181
	s_waitcnt vmcnt(0)
	v_and_b32_e32 v133, 0xffffffc0, v181
	v_mul_lo_u32 v129, v237, s3
	v_lshlrev_b32_e32 v130, 2, v238
	v_and_b32_e32 v128, 60, v128
	v_lshl_add_u32 v176, s8, 8, v133
	v_mul_u32_u24_e32 v133, 0x110, v183
	v_or_b32_e32 v131, v129, v130
	v_lshl_or_b32 v132, v128, 2, v129
	v_lshl_or_b32 v128, s2, 7, v128
	v_lshlrev_b32_e32 v133, 2, v133
	v_lshrrev_b32_e32 v175, 4, v239
	s_movk_i32 s2, 0x110
	v_add_u32_e32 v147, v131, v133
	v_add3_u32 v148, v129, v133, v130
	v_mad_u32_u24 v146, v175, s2, v132
	v_readlane_b32 s2, v254, 39
	v_readlane_b32 s8, v253, 36
	v_add_u32_e32 v149, 0x800, v147
	v_add_u32_e32 v150, 0x800, v148
	v_add_u32_e32 v151, 0xa00, v148
	v_mov_b32_e32 v160, s2
	v_readlane_b32 s2, v254, 37
	v_readlane_b32 s9, v253, 37
	v_readlane_b32 s10, v253, 38
	v_readlane_b32 s11, v253, 39
	v_readlane_b32 s12, v253, 40
	v_readlane_b32 s13, v253, 41
	v_readlane_b32 s14, v253, 42
	v_readlane_b32 s15, v253, 43
	v_readlane_b32 s16, v253, 44
	v_readlane_b32 s17, v253, 45
	ds_write2_b32 v147, v112, v113 offset1:68
	ds_write2_b32 v148, v96, v97 offset0:32 offset1:100
	ds_write2_b32 v147, v114, v115 offset0:136 offset1:204
	ds_write2_b32 v148, v98, v99 offset0:168 offset1:236
	ds_write2_b32 v149, v116, v117 offset0:32 offset1:100
	ds_write2_b32 v150, v100, v101 offset0:64 offset1:132
	ds_write2_b32 v149, v118, v119 offset0:168 offset1:236
	ds_write2_b32 v151, v102, v103 offset0:72 offset1:140
	v_or_b32_e32 v102, v176, v175
	v_mov_b32_e32 v161, s2
	v_readlane_b32 s2, v254, 40
	v_readlane_b32 s18, v253, 46
	v_readlane_b32 s19, v253, 47
	v_readlane_b32 s20, v253, 48
	v_readlane_b32 s21, v253, 49
	v_readlane_b32 s22, v253, 50
	v_readlane_b32 s23, v253, 51
	s_mov_b64 s[8:9], s[16:17]
	v_cmp_gt_i32_e32 vcc, s39, v102
	v_add_u32_e32 v96, 0xffff8000, v102
	v_ashrrev_i32_e32 v97, 31, v102
	v_mov_b32_e32 v162, s2
	v_readlane_b32 s2, v254, 38
	s_mov_b64 s[10:11], s[18:19]
	v_cndmask_b32_e32 v97, 0, v97, vcc
	v_cndmask_b32_e32 v96, v96, v102, vcc
	v_mov_b32_e32 v163, s2
	v_mov_b32_e32 v164, s63
	v_mov_b32_e32 v165, s11
	v_mov_b32_e32 v166, s62
	v_mov_b32_e32 v167, s10
	v_min_i32_e32 v102, 0x8000, v102
	v_add_u32_e32 v152, 0x1000, v147
	v_add_u32_e32 v153, 0x1000, v148
	v_add_u32_e32 v154, 0x1200, v147
	v_add_u32_e32 v155, 0x1200, v148
	v_add_u32_e32 v156, 0x1800, v147
	v_add_u32_e32 v157, 0x1800, v148
	v_add_u32_e32 v158, 0x1a00, v147
	v_add_u32_e32 v159, 0x1c00, v148
	v_ashrrev_i32_e32 v129, 31, v128
	v_cndmask_b32_e32 v99, v160, v161, vcc
	v_cndmask_b32_e32 v98, v162, v163, vcc
	v_lshlrev_b64 v[96:97], 12, v[96:97]
	v_cndmask_b32_e32 v101, v164, v165, vcc
	v_cndmask_b32_e32 v100, v166, v167, vcc
	v_ashrrev_i32_e32 v102, 12, v102
	ds_write2_b32 v152, v120, v121 offset0:64 offset1:132
	ds_write2_b32 v153, v104, v105 offset0:96 offset1:164
	ds_write2_b32 v154, v122, v123 offset0:72 offset1:140
	ds_write2_b32 v155, v106, v107 offset0:104 offset1:172
	ds_write2_b32 v156, v124, v125 offset0:96 offset1:164
	ds_write2_b32 v157, v108, v109 offset0:128 offset1:196
	ds_write2_b32 v158, v126, v127 offset0:104 offset1:172
	ds_write2_b32 v159, v110, v111 offset0:8 offset1:76
	v_lshl_add_u64 v[98:99], v[98:99], 0, v[96:97]
	v_lshl_add_u64 v[100:101], v[100:101], 0, v[96:97]
	v_lshlrev_b64 v[96:97], 2, v[128:129]
	v_mul_hi_i32_i24_e32 v103, 0x6000, v102
	v_mul_i32_i24_e32 v102, 0x6000, v102
	s_waitcnt lgkmcnt(0)
	v_lshl_add_u64 v[98:99], v[98:99], 0, v[96:97]
	v_lshl_add_u64 v[102:103], s[0:1], 0, v[102:103]
	v_lshl_add_u64 v[102:103], v[102:103], 0, v[96:97]
	ds_read_b128 v[104:107], v146
	global_load_dwordx4 v[108:111], v[98:99], off
	global_load_dwordx4 v[112:115], v[102:103], off
	v_or_b32_e32 v168, 4, v175
	v_lshl_add_u64 v[100:101], v[100:101], 0, v[96:97]
	v_or_b32_e32 v169, 8, v175
	v_or_b32_e32 v170, 12, v175
	v_or_b32_e32 v171, 16, v175
	v_or_b32_e32 v172, 20, v175
	v_or_b32_e32 v173, 24, v175
	v_or_b32_e32 v174, 28, v175
	v_or_b32_e32 v181, v176, v174
	v_readlane_b32 s2, v254, 11
	s_add_i32 s4, s4, s2
	s_cmp_lt_i32 s4, s26
	s_mov_b64 s[12:13], s[20:21]
	s_mov_b64 s[14:15], s[22:23]
	s_waitcnt vmcnt(0) lgkmcnt(0)
	v_pk_fma_f32 v[104:105], v[104:105], v[112:113], v[108:109]
	v_pk_fma_f32 v[106:107], v[106:107], v[114:115], v[110:111]
	v_or_b32_e32 v110, v176, v168
	global_store_dwordx4 v[100:101], v[104:107], off
	v_cmp_gt_i32_e32 vcc, s39, v110
	s_nop 0
	v_ashrrev_i32_e32 v104, 31, v110
	v_add_u32_e32 v106, 0xffff8000, v110
	v_cndmask_b32_e32 v105, 0, v104, vcc
	v_cndmask_b32_e32 v104, v106, v110, vcc
	v_cndmask_b32_e32 v107, v160, v161, vcc
	v_cndmask_b32_e32 v106, v162, v163, vcc
	v_lshlrev_b64 v[104:105], 12, v[104:105]
	v_cndmask_b32_e32 v109, v164, v165, vcc
	v_cndmask_b32_e32 v108, v166, v167, vcc
	v_lshl_add_u64 v[106:107], v[106:107], 0, v[104:105]
	v_lshl_add_u64 v[104:105], v[108:109], 0, v[104:105]
	v_min_i32_e32 v108, 0x8000, v110
	v_ashrrev_i32_e32 v108, 12, v108
	v_mul_hi_i32_i24_e32 v109, 0x6000, v108
	v_mul_i32_i24_e32 v108, 0x6000, v108
	v_lshl_add_u64 v[106:107], v[106:107], 0, v[96:97]
	v_lshl_add_u64 v[108:109], s[0:1], 0, v[108:109]
	v_lshl_add_u64 v[108:109], v[108:109], 0, v[96:97]
	ds_read_b128 v[110:113], v146 offset:1088
	global_load_dwordx4 v[114:117], v[106:107], off
	global_load_dwordx4 v[118:121], v[108:109], off
	v_lshl_add_u64 v[104:105], v[104:105], 0, v[96:97]
	s_waitcnt vmcnt(0) lgkmcnt(0)
	v_pk_fma_f32 v[110:111], v[110:111], v[118:119], v[114:115]
	v_pk_fma_f32 v[112:113], v[112:113], v[120:121], v[116:117]
	v_or_b32_e32 v118, v176, v169
	global_store_dwordx4 v[104:105], v[110:113], off
	v_cmp_gt_i32_e32 vcc, s39, v118
	s_nop 0
	v_ashrrev_i32_e32 v110, 31, v118
	v_add_u32_e32 v112, 0xffff8000, v118
	v_cndmask_b32_e32 v111, 0, v110, vcc
	v_cndmask_b32_e32 v110, v112, v118, vcc
	v_cndmask_b32_e32 v113, v160, v161, vcc
	v_cndmask_b32_e32 v112, v162, v163, vcc
	v_lshlrev_b64 v[110:111], 12, v[110:111]
	v_lshl_add_u64 v[112:113], v[112:113], 0, v[110:111]
	v_cndmask_b32_e32 v115, v164, v165, vcc
	v_cndmask_b32_e32 v114, v166, v167, vcc
	v_lshl_add_u64 v[116:117], v[114:115], 0, v[110:111]
	v_lshl_add_u64 v[110:111], v[112:113], 0, v[96:97]
	v_min_i32_e32 v112, 0x8000, v118
	v_ashrrev_i32_e32 v112, 12, v112
	v_mul_hi_i32_i24_e32 v113, 0x6000, v112
	v_mul_i32_i24_e32 v112, 0x6000, v112
	v_lshl_add_u64 v[112:113], s[0:1], 0, v[112:113]
	v_lshl_add_u64 v[114:115], v[112:113], 0, v[96:97]
	v_lshl_add_u64 v[112:113], v[116:117], 0, v[96:97]
	ds_read_b128 v[116:119], v146 offset:2176
	global_load_dwordx4 v[120:123], v[110:111], off
	global_load_dwordx4 v[124:127], v[114:115], off
	s_waitcnt vmcnt(0) lgkmcnt(0)
	v_pk_fma_f32 v[116:117], v[116:117], v[124:125], v[120:121]
	v_pk_fma_f32 v[118:119], v[118:119], v[126:127], v[122:123]
	v_or_b32_e32 v124, v176, v170
	global_store_dwordx4 v[112:113], v[116:119], off
	v_cmp_gt_i32_e32 vcc, s39, v124
	s_nop 0
	v_ashrrev_i32_e32 v116, 31, v124
	v_add_u32_e32 v118, 0xffff8000, v124
	v_cndmask_b32_e32 v117, 0, v116, vcc
	v_cndmask_b32_e32 v116, v118, v124, vcc
	v_cndmask_b32_e32 v119, v160, v161, vcc
	v_cndmask_b32_e32 v118, v162, v163, vcc
	v_lshlrev_b64 v[116:117], 12, v[116:117]
	v_lshl_add_u64 v[118:119], v[118:119], 0, v[116:117]
	v_cndmask_b32_e32 v121, v164, v165, vcc
	v_cndmask_b32_e32 v120, v166, v167, vcc
	v_lshl_add_u64 v[122:123], v[120:121], 0, v[116:117]
	v_lshl_add_u64 v[116:117], v[118:119], 0, v[96:97]
	v_min_i32_e32 v118, 0x8000, v124
	v_ashrrev_i32_e32 v118, 12, v118
	v_mul_hi_i32_i24_e32 v119, 0x6000, v118
	v_mul_i32_i24_e32 v118, 0x6000, v118
	v_lshl_add_u64 v[118:119], s[0:1], 0, v[118:119]
	v_lshl_add_u64 v[120:121], v[118:119], 0, v[96:97]
	v_lshl_add_u64 v[118:119], v[122:123], 0, v[96:97]
	ds_read_b128 v[122:125], v146 offset:3264
	global_load_dwordx4 v[126:129], v[116:117], off
	global_load_dwordx4 v[130:133], v[120:121], off
	s_waitcnt vmcnt(0) lgkmcnt(0)
	v_pk_fma_f32 v[122:123], v[122:123], v[130:131], v[126:127]
	v_pk_fma_f32 v[124:125], v[124:125], v[132:133], v[128:129]
	v_or_b32_e32 v130, v176, v171
	global_store_dwordx4 v[118:119], v[122:125], off
	v_cmp_gt_i32_e32 vcc, s39, v130
	s_nop 0
	v_ashrrev_i32_e32 v122, 31, v130
	v_add_u32_e32 v124, 0xffff8000, v130
	v_cndmask_b32_e32 v123, 0, v122, vcc
	v_cndmask_b32_e32 v122, v124, v130, vcc
	v_cndmask_b32_e32 v125, v160, v161, vcc
	v_cndmask_b32_e32 v124, v162, v163, vcc
	v_lshlrev_b64 v[122:123], 12, v[122:123]
	v_lshl_add_u64 v[124:125], v[124:125], 0, v[122:123]
	v_cndmask_b32_e32 v127, v164, v165, vcc
	v_cndmask_b32_e32 v126, v166, v167, vcc
	v_lshl_add_u64 v[128:129], v[126:127], 0, v[122:123]
	v_lshl_add_u64 v[122:123], v[124:125], 0, v[96:97]
	v_min_i32_e32 v124, 0x8000, v130
	v_ashrrev_i32_e32 v124, 12, v124
	v_mul_hi_i32_i24_e32 v125, 0x6000, v124
	v_mul_i32_i24_e32 v124, 0x6000, v124
	v_lshl_add_u64 v[124:125], s[0:1], 0, v[124:125]
	v_lshl_add_u64 v[126:127], v[124:125], 0, v[96:97]
	v_lshl_add_u64 v[124:125], v[128:129], 0, v[96:97]
	ds_read_b128 v[128:131], v146 offset:4352
	global_load_dwordx4 v[132:135], v[122:123], off
	global_load_dwordx4 v[136:139], v[126:127], off
	s_waitcnt vmcnt(0) lgkmcnt(0)
	v_pk_fma_f32 v[128:129], v[128:129], v[136:137], v[132:133]
	v_pk_fma_f32 v[130:131], v[130:131], v[138:139], v[134:135]
	v_or_b32_e32 v136, v176, v172
	global_store_dwordx4 v[124:125], v[128:131], off
	v_cmp_gt_i32_e32 vcc, s39, v136
	s_nop 0
	v_ashrrev_i32_e32 v128, 31, v136
	v_add_u32_e32 v130, 0xffff8000, v136
	v_cndmask_b32_e32 v129, 0, v128, vcc
	v_cndmask_b32_e32 v128, v130, v136, vcc
	v_cndmask_b32_e32 v131, v160, v161, vcc
	v_cndmask_b32_e32 v130, v162, v163, vcc
	v_lshlrev_b64 v[128:129], 12, v[128:129]
	v_lshl_add_u64 v[130:131], v[130:131], 0, v[128:129]
	v_cndmask_b32_e32 v133, v164, v165, vcc
	v_cndmask_b32_e32 v132, v166, v167, vcc
	v_lshl_add_u64 v[134:135], v[132:133], 0, v[128:129]
	v_lshl_add_u64 v[128:129], v[130:131], 0, v[96:97]
	v_min_i32_e32 v130, 0x8000, v136
	v_ashrrev_i32_e32 v130, 12, v130
	v_mul_hi_i32_i24_e32 v131, 0x6000, v130
	v_mul_i32_i24_e32 v130, 0x6000, v130
	v_lshl_add_u64 v[130:131], s[0:1], 0, v[130:131]
	v_lshl_add_u64 v[132:133], v[130:131], 0, v[96:97]
	v_lshl_add_u64 v[130:131], v[134:135], 0, v[96:97]
	ds_read_b128 v[134:137], v146 offset:5440
	global_load_dwordx4 v[138:141], v[128:129], off
	global_load_dwordx4 v[142:145], v[132:133], off
	s_waitcnt vmcnt(0) lgkmcnt(0)
	v_pk_fma_f32 v[134:135], v[134:135], v[142:143], v[138:139]
	v_pk_fma_f32 v[136:137], v[136:137], v[144:145], v[140:141]
	v_or_b32_e32 v142, v176, v173
	global_store_dwordx4 v[130:131], v[134:137], off
	v_cmp_gt_i32_e32 vcc, s39, v142
	s_nop 0
	v_ashrrev_i32_e32 v134, 31, v142
	v_add_u32_e32 v136, 0xffff8000, v142
	v_cndmask_b32_e32 v135, 0, v134, vcc
	v_cndmask_b32_e32 v134, v136, v142, vcc
	v_cndmask_b32_e32 v137, v160, v161, vcc
	v_cndmask_b32_e32 v136, v162, v163, vcc
	v_lshlrev_b64 v[134:135], 12, v[134:135]
	v_lshl_add_u64 v[136:137], v[136:137], 0, v[134:135]
	v_cndmask_b32_e32 v139, v164, v165, vcc
	v_cndmask_b32_e32 v138, v166, v167, vcc
	v_lshl_add_u64 v[140:141], v[138:139], 0, v[134:135]
	v_lshl_add_u64 v[134:135], v[136:137], 0, v[96:97]
	v_min_i32_e32 v136, 0x8000, v142
	v_ashrrev_i32_e32 v136, 12, v136
	v_mul_hi_i32_i24_e32 v137, 0x6000, v136
	v_mul_i32_i24_e32 v136, 0x6000, v136
	v_lshl_add_u64 v[136:137], s[0:1], 0, v[136:137]
	v_lshl_add_u64 v[138:139], v[136:137], 0, v[96:97]
	v_lshl_add_u64 v[136:137], v[140:141], 0, v[96:97]
	ds_read_b128 v[140:143], v146 offset:6528
	global_load_dwordx4 v[184:187], v[134:135], off
	global_load_dwordx4 v[196:199], v[138:139], off
	v_cmp_gt_i32_e32 vcc, s39, v181
	s_waitcnt vmcnt(0) lgkmcnt(0)
	v_pk_fma_f32 v[140:141], v[140:141], v[196:197], v[184:185]
	v_pk_fma_f32 v[142:143], v[142:143], v[198:199], v[186:187]
	global_store_dwordx4 v[136:137], v[140:143], off
	v_cndmask_b32_e32 v145, v164, v165, vcc
	v_cndmask_b32_e32 v144, v166, v167, vcc
	v_ashrrev_i32_e32 v140, 31, v181
	v_add_u32_e32 v142, 0xffff8000, v181
	v_cndmask_b32_e32 v141, 0, v140, vcc
	v_cndmask_b32_e32 v140, v142, v181, vcc
	v_cndmask_b32_e32 v143, v160, v161, vcc
	v_cndmask_b32_e32 v142, v162, v163, vcc
	v_lshlrev_b64 v[140:141], 12, v[140:141]
	v_lshl_add_u64 v[142:143], v[142:143], 0, v[140:141]
	v_lshl_add_u64 v[184:185], v[144:145], 0, v[140:141]
	v_lshl_add_u64 v[140:141], v[142:143], 0, v[96:97]
	v_min_i32_e32 v142, 0x8000, v181
	v_ashrrev_i32_e32 v142, 12, v142
	v_mul_hi_i32_i24_e32 v143, 0x6000, v142
	v_mul_i32_i24_e32 v142, 0x6000, v142
	v_lshl_add_u64 v[142:143], s[0:1], 0, v[142:143]
	v_lshl_add_u64 v[144:145], v[142:143], 0, v[96:97]
	v_lshl_add_u64 v[142:143], v[184:185], 0, v[96:97]
	ds_read_b128 v[184:187], v146 offset:7616
	global_load_dwordx4 v[196:199], v[140:141], off
	global_load_dwordx4 v[200:203], v[144:145], off
	s_waitcnt vmcnt(0) lgkmcnt(0)
	v_pk_fma_f32 v[184:185], v[184:185], v[200:201], v[196:197]
	v_pk_fma_f32 v[186:187], v[186:187], v[202:203], v[198:199]
	global_store_dwordx4 v[142:143], v[184:187], off
	s_waitcnt lgkmcnt(0)
	ds_write2_b32 v147, v80, v81 offset1:68
	ds_write2_b32 v148, v64, v65 offset0:32 offset1:100
	ds_write2_b32 v147, v82, v83 offset0:136 offset1:204
	ds_write2_b32 v148, v66, v67 offset0:168 offset1:236
	ds_write2_b32 v149, v84, v85 offset0:32 offset1:100
	ds_write2_b32 v150, v68, v69 offset0:64 offset1:132
	ds_write2_b32 v149, v86, v87 offset0:168 offset1:236
	ds_write2_b32 v151, v70, v71 offset0:72 offset1:140
	ds_write2_b32 v152, v88, v89 offset0:64 offset1:132
	ds_write2_b32 v153, v72, v73 offset0:96 offset1:164
	ds_write2_b32 v154, v90, v91 offset0:72 offset1:140
	ds_write2_b32 v155, v74, v75 offset0:104 offset1:172
	ds_write2_b32 v156, v92, v93 offset0:96 offset1:164
	ds_write2_b32 v157, v76, v77 offset0:128 offset1:196
	ds_write2_b32 v158, v94, v95 offset0:104 offset1:172
	ds_write2_b32 v159, v78, v79 offset0:8 offset1:76
	s_waitcnt lgkmcnt(0)
	ds_read_b128 v[64:67], v146
	global_load_dwordx4 v[68:71], v[98:99], off offset:256
	global_load_dwordx4 v[72:75], v[102:103], off offset:256
	s_waitcnt vmcnt(0) lgkmcnt(0)
	v_pk_fma_f32 v[64:65], v[64:65], v[72:73], v[68:69]
	v_pk_fma_f32 v[66:67], v[66:67], v[74:75], v[70:71]
	global_store_dwordx4 v[100:101], v[64:67], off offset:256
	ds_read_b128 v[64:67], v146 offset:1088
	global_load_dwordx4 v[68:71], v[106:107], off offset:256
	global_load_dwordx4 v[72:75], v[108:109], off offset:256
	s_waitcnt vmcnt(0) lgkmcnt(0)
	v_pk_fma_f32 v[64:65], v[64:65], v[72:73], v[68:69]
	v_pk_fma_f32 v[66:67], v[66:67], v[74:75], v[70:71]
	global_store_dwordx4 v[104:105], v[64:67], off offset:256
	ds_read_b128 v[64:67], v146 offset:2176
	global_load_dwordx4 v[68:71], v[110:111], off offset:256
	global_load_dwordx4 v[72:75], v[114:115], off offset:256
	s_waitcnt vmcnt(0) lgkmcnt(0)
	v_pk_fma_f32 v[64:65], v[64:65], v[72:73], v[68:69]
	v_pk_fma_f32 v[66:67], v[66:67], v[74:75], v[70:71]
	global_store_dwordx4 v[112:113], v[64:67], off offset:256
	ds_read_b128 v[64:67], v146 offset:3264
	global_load_dwordx4 v[68:71], v[116:117], off offset:256
	global_load_dwordx4 v[72:75], v[120:121], off offset:256
	s_waitcnt vmcnt(0) lgkmcnt(0)
	v_pk_fma_f32 v[64:65], v[64:65], v[72:73], v[68:69]
	v_pk_fma_f32 v[66:67], v[66:67], v[74:75], v[70:71]
	global_store_dwordx4 v[118:119], v[64:67], off offset:256
	ds_read_b128 v[64:67], v146 offset:4352
	global_load_dwordx4 v[68:71], v[122:123], off offset:256
	global_load_dwordx4 v[72:75], v[126:127], off offset:256
	s_waitcnt vmcnt(0) lgkmcnt(0)
	v_pk_fma_f32 v[64:65], v[64:65], v[72:73], v[68:69]
	v_pk_fma_f32 v[66:67], v[66:67], v[74:75], v[70:71]
	global_store_dwordx4 v[124:125], v[64:67], off offset:256
	ds_read_b128 v[64:67], v146 offset:5440
	global_load_dwordx4 v[68:71], v[128:129], off offset:256
	global_load_dwordx4 v[72:75], v[132:133], off offset:256
	s_waitcnt vmcnt(0) lgkmcnt(0)
	v_pk_fma_f32 v[64:65], v[64:65], v[72:73], v[68:69]
	v_pk_fma_f32 v[66:67], v[66:67], v[74:75], v[70:71]
	global_store_dwordx4 v[130:131], v[64:67], off offset:256
	ds_read_b128 v[64:67], v146 offset:6528
	global_load_dwordx4 v[68:71], v[134:135], off offset:256
	global_load_dwordx4 v[72:75], v[138:139], off offset:256
	s_waitcnt vmcnt(0) lgkmcnt(0)
	v_pk_fma_f32 v[64:65], v[64:65], v[72:73], v[68:69]
	v_pk_fma_f32 v[66:67], v[66:67], v[74:75], v[70:71]
	global_store_dwordx4 v[136:137], v[64:67], off offset:256
	ds_read_b128 v[64:67], v146 offset:7616
	global_load_dwordx4 v[68:71], v[140:141], off offset:256
	global_load_dwordx4 v[72:75], v[144:145], off offset:256
	s_waitcnt vmcnt(0) lgkmcnt(0)
	v_pk_fma_f32 v[64:65], v[64:65], v[72:73], v[68:69]
	v_pk_fma_f32 v[66:67], v[66:67], v[74:75], v[70:71]
	global_store_dwordx4 v[142:143], v[64:67], off offset:256
	v_or_b32_e32 v74, 32, v176
	s_waitcnt lgkmcnt(0)
	ds_write2_b32 v147, v48, v49 offset1:68
	ds_write2_b32 v148, v32, v33 offset0:32 offset1:100
	ds_write2_b32 v147, v50, v51 offset0:136 offset1:204
	ds_write2_b32 v148, v34, v35 offset0:168 offset1:236
	ds_write2_b32 v149, v52, v53 offset0:32 offset1:100
	ds_write2_b32 v150, v36, v37 offset0:64 offset1:132
	ds_write2_b32 v149, v54, v55 offset0:168 offset1:236
	ds_write2_b32 v151, v38, v39 offset0:72 offset1:140
	ds_write2_b32 v152, v56, v57 offset0:64 offset1:132
	ds_write2_b32 v153, v40, v41 offset0:96 offset1:164
	ds_write2_b32 v154, v58, v59 offset0:72 offset1:140
	ds_write2_b32 v155, v42, v43 offset0:104 offset1:172
	ds_write2_b32 v156, v60, v61 offset0:96 offset1:164
	ds_write2_b32 v157, v44, v45 offset0:128 offset1:196
	ds_write2_b32 v158, v62, v63 offset0:104 offset1:172
	ds_write2_b32 v159, v46, v47 offset0:8 offset1:76
	v_or_b32_e32 v40, v74, v175
	v_cmp_gt_i32_e32 vcc, s39, v40
	v_ashrrev_i32_e32 v32, 31, v40
	v_add_u32_e32 v34, 0xffff8000, v40
	v_cndmask_b32_e32 v33, 0, v32, vcc
	v_cndmask_b32_e32 v32, v34, v40, vcc
	v_cndmask_b32_e32 v35, v160, v161, vcc
	v_cndmask_b32_e32 v34, v162, v163, vcc
	v_lshlrev_b64 v[32:33], 12, v[32:33]
	v_lshl_add_u64 v[34:35], v[34:35], 0, v[32:33]
	v_cndmask_b32_e32 v37, v164, v165, vcc
	v_cndmask_b32_e32 v36, v166, v167, vcc
	v_lshl_add_u64 v[38:39], v[36:37], 0, v[32:33]
	v_lshl_add_u64 v[32:33], v[34:35], 0, v[96:97]
	v_min_i32_e32 v34, 0x8000, v40
	v_ashrrev_i32_e32 v34, 12, v34
	v_mul_hi_i32_i24_e32 v35, 0x6000, v34
	v_mul_i32_i24_e32 v34, 0x6000, v34
	s_waitcnt lgkmcnt(0)
	v_lshl_add_u64 v[34:35], s[0:1], 0, v[34:35]
	v_lshl_add_u64 v[36:37], v[34:35], 0, v[96:97]
	v_lshl_add_u64 v[34:35], v[38:39], 0, v[96:97]
	ds_read_b128 v[38:41], v146
	global_load_dwordx4 v[42:45], v[32:33], off
	global_load_dwordx4 v[46:49], v[36:37], off
	v_or_b32_e32 v75, v74, v173
	s_waitcnt vmcnt(0) lgkmcnt(0)
	v_pk_fma_f32 v[38:39], v[38:39], v[46:47], v[42:43]
	v_pk_fma_f32 v[40:41], v[40:41], v[48:49], v[44:45]
	v_or_b32_e32 v46, v74, v168
	global_store_dwordx4 v[34:35], v[38:41], off
	v_cmp_gt_i32_e32 vcc, s39, v46
	s_nop 0
	v_ashrrev_i32_e32 v38, 31, v46
	v_add_u32_e32 v40, 0xffff8000, v46
	v_cndmask_b32_e32 v39, 0, v38, vcc
	v_cndmask_b32_e32 v38, v40, v46, vcc
	v_cndmask_b32_e32 v41, v160, v161, vcc
	v_cndmask_b32_e32 v40, v162, v163, vcc
	v_lshlrev_b64 v[38:39], 12, v[38:39]
	v_lshl_add_u64 v[40:41], v[40:41], 0, v[38:39]
	v_cndmask_b32_e32 v43, v164, v165, vcc
	v_cndmask_b32_e32 v42, v166, v167, vcc
	v_lshl_add_u64 v[44:45], v[42:43], 0, v[38:39]
	v_lshl_add_u64 v[38:39], v[40:41], 0, v[96:97]
	v_min_i32_e32 v40, 0x8000, v46
	v_ashrrev_i32_e32 v40, 12, v40
	v_mul_hi_i32_i24_e32 v41, 0x6000, v40
	v_mul_i32_i24_e32 v40, 0x6000, v40
	v_lshl_add_u64 v[40:41], s[0:1], 0, v[40:41]
	v_lshl_add_u64 v[42:43], v[40:41], 0, v[96:97]
	v_lshl_add_u64 v[40:41], v[44:45], 0, v[96:97]
	ds_read_b128 v[44:47], v146 offset:1088
	global_load_dwordx4 v[48:51], v[38:39], off
	global_load_dwordx4 v[52:55], v[42:43], off
	s_waitcnt vmcnt(0) lgkmcnt(0)
	v_pk_fma_f32 v[44:45], v[44:45], v[52:53], v[48:49]
	v_pk_fma_f32 v[46:47], v[46:47], v[54:55], v[50:51]
	v_or_b32_e32 v52, v74, v169
	global_store_dwordx4 v[40:41], v[44:47], off
	v_cmp_gt_i32_e32 vcc, s39, v52
	s_nop 0
	v_ashrrev_i32_e32 v44, 31, v52
	v_add_u32_e32 v46, 0xffff8000, v52
	v_cndmask_b32_e32 v45, 0, v44, vcc
	v_cndmask_b32_e32 v44, v46, v52, vcc
	v_cndmask_b32_e32 v47, v160, v161, vcc
	v_cndmask_b32_e32 v46, v162, v163, vcc
	v_lshlrev_b64 v[44:45], 12, v[44:45]
	v_lshl_add_u64 v[46:47], v[46:47], 0, v[44:45]
	v_cndmask_b32_e32 v49, v164, v165, vcc
	v_cndmask_b32_e32 v48, v166, v167, vcc
	v_lshl_add_u64 v[50:51], v[48:49], 0, v[44:45]
	v_lshl_add_u64 v[44:45], v[46:47], 0, v[96:97]
	v_min_i32_e32 v46, 0x8000, v52
	v_ashrrev_i32_e32 v46, 12, v46
	v_mul_hi_i32_i24_e32 v47, 0x6000, v46
	v_mul_i32_i24_e32 v46, 0x6000, v46
	v_lshl_add_u64 v[46:47], s[0:1], 0, v[46:47]
	v_lshl_add_u64 v[48:49], v[46:47], 0, v[96:97]
	v_lshl_add_u64 v[46:47], v[50:51], 0, v[96:97]
	ds_read_b128 v[50:53], v146 offset:2176
	global_load_dwordx4 v[54:57], v[44:45], off
	global_load_dwordx4 v[58:61], v[48:49], off
	s_waitcnt vmcnt(0) lgkmcnt(0)
	v_pk_fma_f32 v[50:51], v[50:51], v[58:59], v[54:55]
	v_pk_fma_f32 v[52:53], v[52:53], v[60:61], v[56:57]
	v_or_b32_e32 v58, v74, v170
	global_store_dwordx4 v[46:47], v[50:53], off
	v_cmp_gt_i32_e32 vcc, s39, v58
	s_nop 0
	v_ashrrev_i32_e32 v50, 31, v58
	v_add_u32_e32 v52, 0xffff8000, v58
	v_cndmask_b32_e32 v51, 0, v50, vcc
	v_cndmask_b32_e32 v50, v52, v58, vcc
	v_cndmask_b32_e32 v53, v160, v161, vcc
	v_cndmask_b32_e32 v52, v162, v163, vcc
	v_lshlrev_b64 v[50:51], 12, v[50:51]
	v_lshl_add_u64 v[52:53], v[52:53], 0, v[50:51]
	v_cndmask_b32_e32 v55, v164, v165, vcc
	v_cndmask_b32_e32 v54, v166, v167, vcc
	v_lshl_add_u64 v[56:57], v[54:55], 0, v[50:51]
	v_lshl_add_u64 v[50:51], v[52:53], 0, v[96:97]
	v_min_i32_e32 v52, 0x8000, v58
	v_ashrrev_i32_e32 v52, 12, v52
	v_mul_hi_i32_i24_e32 v53, 0x6000, v52
	v_mul_i32_i24_e32 v52, 0x6000, v52
	v_lshl_add_u64 v[52:53], s[0:1], 0, v[52:53]
	v_lshl_add_u64 v[54:55], v[52:53], 0, v[96:97]
	v_lshl_add_u64 v[52:53], v[56:57], 0, v[96:97]
	ds_read_b128 v[56:59], v146 offset:3264
	global_load_dwordx4 v[60:63], v[50:51], off
	global_load_dwordx4 v[64:67], v[54:55], off
	s_waitcnt vmcnt(0) lgkmcnt(0)
	v_pk_fma_f32 v[56:57], v[56:57], v[64:65], v[60:61]
	v_pk_fma_f32 v[58:59], v[58:59], v[66:67], v[62:63]
	v_or_b32_e32 v64, v74, v171
	global_store_dwordx4 v[52:53], v[56:59], off
	v_cmp_gt_i32_e32 vcc, s39, v64
	s_nop 0
	v_ashrrev_i32_e32 v56, 31, v64
	v_add_u32_e32 v58, 0xffff8000, v64
	v_cndmask_b32_e32 v57, 0, v56, vcc
	v_cndmask_b32_e32 v56, v58, v64, vcc
	v_cndmask_b32_e32 v59, v160, v161, vcc
	v_cndmask_b32_e32 v58, v162, v163, vcc
	v_lshlrev_b64 v[56:57], 12, v[56:57]
	v_lshl_add_u64 v[58:59], v[58:59], 0, v[56:57]
	v_cndmask_b32_e32 v61, v164, v165, vcc
	v_cndmask_b32_e32 v60, v166, v167, vcc
	v_lshl_add_u64 v[62:63], v[60:61], 0, v[56:57]
	v_lshl_add_u64 v[56:57], v[58:59], 0, v[96:97]
	v_min_i32_e32 v58, 0x8000, v64
	v_ashrrev_i32_e32 v58, 12, v58
	v_mul_hi_i32_i24_e32 v59, 0x6000, v58
	v_mul_i32_i24_e32 v58, 0x6000, v58
	v_lshl_add_u64 v[58:59], s[0:1], 0, v[58:59]
	v_lshl_add_u64 v[60:61], v[58:59], 0, v[96:97]
	v_lshl_add_u64 v[58:59], v[62:63], 0, v[96:97]
	ds_read_b128 v[62:65], v146 offset:4352
	global_load_dwordx4 v[66:69], v[56:57], off
	global_load_dwordx4 v[70:73], v[60:61], off
	s_waitcnt vmcnt(0) lgkmcnt(0)
	v_pk_fma_f32 v[62:63], v[62:63], v[70:71], v[66:67]
	v_pk_fma_f32 v[64:65], v[64:65], v[72:73], v[68:69]
	v_or_b32_e32 v70, v74, v172
	global_store_dwordx4 v[58:59], v[62:65], off
	v_cmp_gt_i32_e32 vcc, s39, v70
	s_nop 0
	v_ashrrev_i32_e32 v62, 31, v70
	v_add_u32_e32 v64, 0xffff8000, v70
	v_cndmask_b32_e32 v63, 0, v62, vcc
	v_cndmask_b32_e32 v62, v64, v70, vcc
	v_cndmask_b32_e32 v65, v160, v161, vcc
	v_cndmask_b32_e32 v64, v162, v163, vcc
	v_lshlrev_b64 v[62:63], 12, v[62:63]
	v_lshl_add_u64 v[64:65], v[64:65], 0, v[62:63]
	v_cndmask_b32_e32 v67, v164, v165, vcc
	v_cndmask_b32_e32 v66, v166, v167, vcc
	v_lshl_add_u64 v[68:69], v[66:67], 0, v[62:63]
	v_lshl_add_u64 v[62:63], v[64:65], 0, v[96:97]
	v_min_i32_e32 v64, 0x8000, v70
	v_ashrrev_i32_e32 v64, 12, v64
	v_mul_hi_i32_i24_e32 v65, 0x6000, v64
	v_mul_i32_i24_e32 v64, 0x6000, v64
	v_lshl_add_u64 v[64:65], s[0:1], 0, v[64:65]
	v_lshl_add_u64 v[66:67], v[64:65], 0, v[96:97]
	v_lshl_add_u64 v[64:65], v[68:69], 0, v[96:97]
	ds_read_b128 v[68:71], v146 offset:5440
	global_load_dwordx4 v[76:79], v[62:63], off
	global_load_dwordx4 v[80:83], v[66:67], off
	v_cmp_gt_i32_e32 vcc, s39, v75
	s_waitcnt vmcnt(0) lgkmcnt(0)
	v_pk_fma_f32 v[68:69], v[68:69], v[80:81], v[76:77]
	v_pk_fma_f32 v[70:71], v[70:71], v[82:83], v[78:79]
	global_store_dwordx4 v[64:65], v[68:71], off
	v_cndmask_b32_e32 v73, v164, v165, vcc
	v_cndmask_b32_e32 v72, v166, v167, vcc
	v_ashrrev_i32_e32 v68, 31, v75
	v_add_u32_e32 v70, 0xffff8000, v75
	v_cndmask_b32_e32 v69, 0, v68, vcc
	v_cndmask_b32_e32 v68, v70, v75, vcc
	v_cndmask_b32_e32 v71, v160, v161, vcc
	v_cndmask_b32_e32 v70, v162, v163, vcc
	v_lshlrev_b64 v[68:69], 12, v[68:69]
	v_lshl_add_u64 v[70:71], v[70:71], 0, v[68:69]
	v_lshl_add_u64 v[76:77], v[72:73], 0, v[68:69]
	v_lshl_add_u64 v[68:69], v[70:71], 0, v[96:97]
	v_min_i32_e32 v70, 0x8000, v75
	v_ashrrev_i32_e32 v70, 12, v70
	v_mul_hi_i32_i24_e32 v71, 0x6000, v70
	v_mul_i32_i24_e32 v70, 0x6000, v70
	v_lshl_add_u64 v[70:71], s[0:1], 0, v[70:71]
	v_lshl_add_u64 v[72:73], v[70:71], 0, v[96:97]
	v_lshl_add_u64 v[70:71], v[76:77], 0, v[96:97]
	ds_read_b128 v[76:79], v146 offset:6528
	global_load_dwordx4 v[80:83], v[68:69], off
	global_load_dwordx4 v[84:87], v[72:73], off
	s_waitcnt vmcnt(0) lgkmcnt(0)
	v_pk_fma_f32 v[76:77], v[76:77], v[84:85], v[80:81]
	v_pk_fma_f32 v[78:79], v[78:79], v[86:87], v[82:83]
	v_or_b32_e32 v82, v74, v174
	global_store_dwordx4 v[70:71], v[76:79], off
	v_cmp_gt_i32_e32 vcc, s39, v82
	v_ashrrev_i32_e32 v74, 31, v82
	v_add_u32_e32 v76, 0xffff8000, v82
	v_cndmask_b32_e32 v75, 0, v74, vcc
	v_cndmask_b32_e32 v74, v76, v82, vcc
	v_cndmask_b32_e32 v77, v160, v161, vcc
	v_cndmask_b32_e32 v76, v162, v163, vcc
	v_lshlrev_b64 v[74:75], 12, v[74:75]
	v_lshl_add_u64 v[76:77], v[76:77], 0, v[74:75]
	v_cndmask_b32_e32 v79, v164, v165, vcc
	v_cndmask_b32_e32 v78, v166, v167, vcc
	v_lshl_add_u64 v[80:81], v[78:79], 0, v[74:75]
	v_lshl_add_u64 v[74:75], v[76:77], 0, v[96:97]
	v_min_i32_e32 v76, 0x8000, v82
	v_ashrrev_i32_e32 v76, 12, v76
	v_mul_hi_i32_i24_e32 v77, 0x6000, v76
	v_mul_i32_i24_e32 v76, 0x6000, v76
	v_lshl_add_u64 v[76:77], s[0:1], 0, v[76:77]
	v_lshl_add_u64 v[78:79], v[76:77], 0, v[96:97]
	v_lshl_add_u64 v[76:77], v[80:81], 0, v[96:97]
	ds_read_b128 v[80:83], v146 offset:7616
	global_load_dwordx4 v[84:87], v[74:75], off
	global_load_dwordx4 v[88:91], v[78:79], off
	s_waitcnt vmcnt(0) lgkmcnt(0)
	v_pk_fma_f32 v[80:81], v[80:81], v[88:89], v[84:85]
	v_pk_fma_f32 v[82:83], v[82:83], v[90:91], v[86:87]
	global_store_dwordx4 v[76:77], v[80:83], off
	s_waitcnt lgkmcnt(0)
	ds_write2_b32 v147, v16, v17 offset1:68
	ds_write2_b32 v148, v0, v1 offset0:32 offset1:100
	ds_write2_b32 v147, v18, v19 offset0:136 offset1:204
	ds_write2_b32 v148, v2, v3 offset0:168 offset1:236
	ds_write2_b32 v149, v20, v21 offset0:32 offset1:100
	ds_write2_b32 v150, v4, v5 offset0:64 offset1:132
	ds_write2_b32 v149, v22, v23 offset0:168 offset1:236
	ds_write2_b32 v151, v6, v7 offset0:72 offset1:140
	ds_write2_b32 v152, v24, v25 offset0:64 offset1:132
	ds_write2_b32 v153, v8, v9 offset0:96 offset1:164
	ds_write2_b32 v154, v26, v27 offset0:72 offset1:140
	ds_write2_b32 v155, v10, v11 offset0:104 offset1:172
	ds_write2_b32 v156, v28, v29 offset0:96 offset1:164
	ds_write2_b32 v157, v12, v13 offset0:128 offset1:196
	ds_write2_b32 v158, v30, v31 offset0:104 offset1:172
	ds_write2_b32 v159, v14, v15 offset0:8 offset1:76
	s_waitcnt lgkmcnt(0)
	ds_read_b128 v[0:3], v146
	global_load_dwordx4 v[4:7], v[32:33], off offset:256
	global_load_dwordx4 v[8:11], v[36:37], off offset:256
	s_waitcnt vmcnt(0) lgkmcnt(0)
	v_pk_fma_f32 v[0:1], v[0:1], v[8:9], v[4:5]
	v_pk_fma_f32 v[2:3], v[2:3], v[10:11], v[6:7]
	global_store_dwordx4 v[34:35], v[0:3], off offset:256
	ds_read_b128 v[0:3], v146 offset:1088
	global_load_dwordx4 v[4:7], v[38:39], off offset:256
	global_load_dwordx4 v[8:11], v[42:43], off offset:256
	s_waitcnt vmcnt(0) lgkmcnt(0)
	v_pk_fma_f32 v[0:1], v[0:1], v[8:9], v[4:5]
	v_pk_fma_f32 v[2:3], v[2:3], v[10:11], v[6:7]
	global_store_dwordx4 v[40:41], v[0:3], off offset:256
	ds_read_b128 v[0:3], v146 offset:2176
	global_load_dwordx4 v[4:7], v[44:45], off offset:256
	global_load_dwordx4 v[8:11], v[48:49], off offset:256
	s_waitcnt vmcnt(0) lgkmcnt(0)
	v_pk_fma_f32 v[0:1], v[0:1], v[8:9], v[4:5]
	v_pk_fma_f32 v[2:3], v[2:3], v[10:11], v[6:7]
	global_store_dwordx4 v[46:47], v[0:3], off offset:256
	ds_read_b128 v[0:3], v146 offset:3264
	global_load_dwordx4 v[4:7], v[50:51], off offset:256
	global_load_dwordx4 v[8:11], v[54:55], off offset:256
	s_waitcnt vmcnt(0) lgkmcnt(0)
	v_pk_fma_f32 v[0:1], v[0:1], v[8:9], v[4:5]
	v_pk_fma_f32 v[2:3], v[2:3], v[10:11], v[6:7]
	global_store_dwordx4 v[52:53], v[0:3], off offset:256
	ds_read_b128 v[0:3], v146 offset:4352
	global_load_dwordx4 v[4:7], v[56:57], off offset:256
	global_load_dwordx4 v[8:11], v[60:61], off offset:256
	s_waitcnt vmcnt(0) lgkmcnt(0)
	v_pk_fma_f32 v[0:1], v[0:1], v[8:9], v[4:5]
	v_pk_fma_f32 v[2:3], v[2:3], v[10:11], v[6:7]
	global_store_dwordx4 v[58:59], v[0:3], off offset:256
	ds_read_b128 v[0:3], v146 offset:5440
	global_load_dwordx4 v[4:7], v[62:63], off offset:256
	global_load_dwordx4 v[8:11], v[66:67], off offset:256
	s_waitcnt vmcnt(0) lgkmcnt(0)
	v_pk_fma_f32 v[0:1], v[0:1], v[8:9], v[4:5]
	v_pk_fma_f32 v[2:3], v[2:3], v[10:11], v[6:7]
	global_store_dwordx4 v[64:65], v[0:3], off offset:256
	ds_read_b128 v[0:3], v146 offset:6528
	global_load_dwordx4 v[4:7], v[68:69], off offset:256
	global_load_dwordx4 v[8:11], v[72:73], off offset:256
	s_waitcnt vmcnt(0) lgkmcnt(0)
	v_pk_fma_f32 v[0:1], v[0:1], v[8:9], v[4:5]
	v_pk_fma_f32 v[2:3], v[2:3], v[10:11], v[6:7]
	global_store_dwordx4 v[70:71], v[0:3], off offset:256
	ds_read_b128 v[0:3], v146 offset:7616
	global_load_dwordx4 v[4:7], v[74:75], off offset:256
	global_load_dwordx4 v[8:11], v[78:79], off offset:256
	s_waitcnt vmcnt(0) lgkmcnt(0)
	v_pk_fma_f32 v[0:1], v[0:1], v[8:9], v[4:5]
	v_pk_fma_f32 v[2:3], v[2:3], v[10:11], v[6:7]
	global_store_dwordx4 v[76:77], v[0:3], off offset:256
	s_waitcnt lgkmcnt(0)
	s_barrier
	s_cbranch_scc1 .LBB0_923

.LBB0_1032:
	s_add_i32 s8, s1, 4
	s_min_u32 s9, s8, 31
	s_lshl_b32 s96, s9, 13
	v_lshl_add_u64 v[168:169], v[186:187], 0, s[96:97]
	v_add_co_u32_e32 v172, vcc, s85, v168
	s_add_i32 s8, s1, 2
	s_nop 0
	v_addc_co_u32_e32 v173, vcc, 0, v169, vcc
	ds_read_b128 v[196:199], v241
	ds_read_b128 v[200:203], v241 offset:2560
	ds_read_b128 v[204:207], v241 offset:5120
	ds_read_b128 v[242:245], v241 offset:7680
	global_load_dwordx4 v[168:171], v[168:169], off
	s_nop 0
	global_load_dwordx4 v[172:175], v[172:173], off
	s_lshl_b32 s96, s9, 11
	s_waitcnt vmcnt(10) lgkmcnt(3)
	v_mfma_f32_32x32x16_bf16 v[112:127], v[160:163], v[196:199], v[112:127]
	s_min_u32 s1, s8, 28
	s_add_i32 s1, s1, 3
	s_waitcnt lgkmcnt(2)
	v_mfma_f32_32x32x16_bf16 v[96:111], v[160:163], v[200:203], v[96:111]
	s_waitcnt vmcnt(7)
	v_mfma_f32_32x32x16_bf16 v[80:95], v[164:167], v[196:199], v[80:95]
	ds_read_b128 v[196:199], v241 offset:5152
	s_waitcnt lgkmcnt(2)
	v_mfma_f32_32x32x16_bf16 v[48:63], v[160:163], v[204:207], v[48:63]
	v_mfma_f32_32x32x16_bf16 v[64:79], v[164:167], v[200:203], v[64:79]
	ds_read_b128 v[200:203], v241 offset:7712
	s_waitcnt lgkmcnt(2)
	v_mfma_f32_32x32x16_bf16 v[32:47], v[160:163], v[242:245], v[32:47]
	ds_read_b128 v[160:163], v241 offset:32
	v_mfma_f32_32x32x16_bf16 v[16:31], v[164:167], v[204:207], v[16:31]
	v_mfma_f32_32x32x16_bf16 v[0:15], v[164:167], v[242:245], v[0:15]
	ds_read_b128 v[164:167], v241 offset:2592
	s_waitcnt vmcnt(3)
	ds_write_b128 v188, v[140:143] offset:10240
	s_waitcnt vmcnt(2)
	ds_write_b128 v188, v[144:147] offset:15360
	v_lshl_add_u64 v[140:141], v[184:185], 0, s[96:97]
	v_add_co_u32_e32 v142, vcc, s41, v140
	s_lshl_b32 s96, s1, 13
	s_nop 0
	v_addc_co_u32_e32 v143, vcc, 0, v141, vcc
	v_lshl_add_u64 v[144:145], v[186:187], 0, s[96:97]
	v_add_co_u32_e32 v146, vcc, s85, v144
	s_waitcnt lgkmcnt(3)
	v_mfma_f32_32x32x16_bf16 v[112:127], v[148:151], v[160:163], v[112:127]
	v_addc_co_u32_e32 v147, vcc, 0, v145, vcc
	s_waitcnt lgkmcnt(2)
	v_mfma_f32_32x32x16_bf16 v[96:111], v[148:151], v[164:167], v[96:111]
	v_mfma_f32_32x32x16_bf16 v[48:63], v[148:151], v[196:199], v[48:63]
	v_mfma_f32_32x32x16_bf16 v[32:47], v[148:151], v[200:203], v[32:47]
	v_mfma_f32_32x32x16_bf16 v[80:95], v[128:131], v[160:163], v[80:95]
	v_mfma_f32_32x32x16_bf16 v[64:79], v[128:131], v[164:167], v[64:79]
	global_load_dwordx4 v[164:167], v[142:143], off
	global_load_dwordx4 v[160:163], v[140:141], off
	global_load_dwordx4 v[148:151], v[140:141], off offset:1024
	v_mfma_f32_32x32x16_bf16 v[16:31], v[128:131], v[196:199], v[16:31]
	v_mfma_f32_32x32x16_bf16 v[0:15], v[128:131], v[200:203], v[0:15]
	global_load_dwordx4 v[128:131], v[142:143], off offset:1024
	s_waitcnt lgkmcnt(0)
	s_barrier
	ds_read_b128 v[196:199], v241 offset:10240
	ds_read_b128 v[200:203], v241 offset:12800
	ds_read_b128 v[204:207], v241 offset:15360
	ds_read_b128 v[242:245], v241 offset:17920
	global_load_dwordx4 v[140:143], v[144:145], off
	s_nop 0
	global_load_dwordx4 v[144:147], v[146:147], off
	s_lshl_b32 s96, s1, 11
	s_waitcnt lgkmcnt(3)
	v_mfma_f32_32x32x16_bf16 v[112:127], v[152:155], v[196:199], v[112:127]
	s_mov_b32 s1, s8
	s_cmp_lt_u32 s8, 30
	s_waitcnt lgkmcnt(2)
	v_mfma_f32_32x32x16_bf16 v[96:111], v[152:155], v[200:203], v[96:111]
	v_mfma_f32_32x32x16_bf16 v[80:95], v[156:159], v[196:199], v[80:95]
	ds_read_b128 v[196:199], v241 offset:15392
	s_waitcnt lgkmcnt(2)
	v_mfma_f32_32x32x16_bf16 v[48:63], v[152:155], v[204:207], v[48:63]
	v_mfma_f32_32x32x16_bf16 v[64:79], v[156:159], v[200:203], v[64:79]
	ds_read_b128 v[200:203], v241 offset:17952
	s_waitcnt lgkmcnt(2)
	v_mfma_f32_32x32x16_bf16 v[32:47], v[152:155], v[242:245], v[32:47]
	ds_read_b128 v[152:155], v241 offset:10272
	v_mfma_f32_32x32x16_bf16 v[16:31], v[156:159], v[204:207], v[16:31]
	v_mfma_f32_32x32x16_bf16 v[0:15], v[156:159], v[242:245], v[0:15]
	ds_read_b128 v[156:159], v241 offset:12832
	s_waitcnt lgkmcnt(1)
	v_mfma_f32_32x32x16_bf16 v[112:127], v[136:139], v[152:155], v[112:127]
	s_waitcnt lgkmcnt(0)
	v_mfma_f32_32x32x16_bf16 v[96:111], v[136:139], v[156:159], v[96:111]
	v_mfma_f32_32x32x16_bf16 v[48:63], v[136:139], v[196:199], v[48:63]
	v_mfma_f32_32x32x16_bf16 v[32:47], v[136:139], v[200:203], v[32:47]
	v_lshl_add_u64 v[136:137], v[184:185], 0, s[96:97]
	v_mfma_f32_32x32x16_bf16 v[16:31], v[132:135], v[196:199], v[16:31]
	v_add_co_u32_e32 v196, vcc, s41, v136
	s_nop 1
	v_addc_co_u32_e32 v197, vcc, 0, v137, vcc
	v_mfma_f32_32x32x16_bf16 v[80:95], v[132:135], v[152:155], v[80:95]
	v_mfma_f32_32x32x16_bf16 v[64:79], v[132:135], v[156:159], v[64:79]
	global_load_dwordx4 v[156:159], v[196:197], off
	global_load_dwordx4 v[152:155], v[136:137], off
	s_nop 0
	global_load_dwordx4 v[136:139], v[136:137], off offset:1024
	v_mfma_f32_32x32x16_bf16 v[0:15], v[132:135], v[200:203], v[0:15]
	global_load_dwordx4 v[132:135], v[196:197], off offset:1024
	s_waitcnt vmcnt(11)
	ds_write_b128 v188, v[168:171]
	s_waitcnt vmcnt(10)
	ds_write_b128 v188, v[172:175] offset:5120
	s_waitcnt lgkmcnt(0)
	s_barrier
	s_cbranch_scc1 .LBB0_1032
	s_waitcnt vmcnt(0)
	v_mul_f32_e32 v133, 0xbfb8aa3b, v112
	v_exp_f32_e32 v133, v133
	s_movk_i32 s1, 0x2400
	v_mul_lo_u32 v128, v238, s1
	v_lshl_or_b32 v131, s0, 6, v181
	v_add_f32_e32 v133, 1.0, v133
	v_lshl_or_b32 v132, v239, 1, v128
	v_and_b32_e32 v129, 0xffffffc0, v237
	v_lshl_or_b32 v128, v181, 1, v128
	v_rcp_f32_e32 v135, v133
	s_nop 0
	v_mul_f32_e32 v112, v112, v135
	v_mul_f32_e32 v96, v96, v112
	v_cvt_pk_bf16_f32 v112, v96, s0
	s_movk_i32 s0, 0x240
	v_mad_u32_u24 v96, v183, s0, v132
	ds_write_b16 v96, v112
	v_mul_f32_e32 v112, 0xbfb8aa3b, v113
	v_exp_f32_e32 v112, v112
	v_lshl_add_u32 v130, s7, 8, v129
	v_lshrrev_b32_e32 v129, 2, v240
	v_mad_u32_u24 v128, v129, s42, v128
	v_add_f32_e32 v112, 1.0, v112
	v_rcp_f32_e32 v133, v112
	s_nop 0
	v_mul_f32_e32 v112, v113, v133
	v_mul_f32_e32 v97, v97, v112
	v_cvt_pk_bf16_f32 v97, v97, s0
	ds_write_b16 v96, v97 offset:144
	v_mul_f32_e32 v97, 0xbfb8aa3b, v114
	v_exp_f32_e32 v97, v97
	s_nop 0
	v_add_f32_e32 v97, 1.0, v97
	v_rcp_f32_e32 v113, v97
	s_nop 0
	v_mul_f32_e32 v97, v114, v113
	v_mul_f32_e32 v97, v98, v97
	v_cvt_pk_bf16_f32 v97, v97, s0
	ds_write_b16 v96, v97 offset:288
	v_mul_f32_e32 v97, 0xbfb8aa3b, v115
	v_exp_f32_e32 v97, v97
	s_nop 0
	v_add_f32_e32 v97, 1.0, v97
	v_rcp_f32_e32 v112, v97
	s_nop 0
	v_mul_f32_e32 v97, v115, v112
	v_mul_f32_e32 v97, v99, v97
	v_cvt_pk_bf16_f32 v97, v97, s0
	ds_write_b16 v96, v97 offset:432
	v_mul_f32_e32 v97, 0xbfb8aa3b, v116
	v_exp_f32_e32 v97, v97
	s_nop 0
	v_add_f32_e32 v97, 1.0, v97
	v_rcp_f32_e32 v99, v97
	s_nop 0
	v_mul_f32_e32 v97, v116, v99
	v_mul_f32_e32 v97, v100, v97
	v_cvt_pk_bf16_f32 v97, v97, s0
	ds_write_b16 v96, v97 offset:1152
	v_mul_f32_e32 v97, 0xbfb8aa3b, v117
	v_exp_f32_e32 v97, v97
	s_nop 0
	v_add_f32_e32 v97, 1.0, v97
	v_rcp_f32_e32 v99, v97
	s_nop 0
	v_mul_f32_e32 v97, v117, v99
	v_mul_f32_e32 v97, v101, v97
	v_cvt_pk_bf16_f32 v97, v97, s0
	ds_write_b16 v96, v97 offset:1296
	v_mul_f32_e32 v97, 0xbfb8aa3b, v118
	v_exp_f32_e32 v97, v97
	s_nop 0
	v_add_f32_e32 v97, 1.0, v97
	v_rcp_f32_e32 v99, v97
	s_nop 0
	v_mul_f32_e32 v97, v118, v99
	v_mul_f32_e32 v97, v102, v97
	v_cvt_pk_bf16_f32 v97, v97, s0
	ds_write_b16 v96, v97 offset:1440
	v_mul_f32_e32 v97, 0xbfb8aa3b, v119
	v_exp_f32_e32 v97, v97
	s_nop 0
	v_add_f32_e32 v97, 1.0, v97
	v_rcp_f32_e32 v99, v97
	s_nop 0
	v_mul_f32_e32 v97, v119, v99
	v_mul_f32_e32 v97, v103, v97
	v_cvt_pk_bf16_f32 v97, v97, s0
	ds_write_b16 v96, v97 offset:1584
	v_mul_f32_e32 v97, 0xbfb8aa3b, v120
	v_exp_f32_e32 v97, v97
	s_nop 0
	v_add_f32_e32 v97, 1.0, v97
	v_rcp_f32_e32 v99, v97
	s_nop 0
	v_mul_f32_e32 v97, v120, v99
	v_mul_f32_e32 v97, v104, v97
	v_cvt_pk_bf16_f32 v97, v97, s0
	ds_write_b16 v96, v97 offset:2304
	v_mul_f32_e32 v97, 0xbfb8aa3b, v121
	v_exp_f32_e32 v97, v97
	s_nop 0
	v_add_f32_e32 v97, 1.0, v97
	v_rcp_f32_e32 v99, v97
	s_nop 0
	v_mul_f32_e32 v97, v121, v99
	v_mul_f32_e32 v97, v105, v97
	v_cvt_pk_bf16_f32 v97, v97, s0
	ds_write_b16 v96, v97 offset:2448
	v_mul_f32_e32 v97, 0xbfb8aa3b, v122
	v_exp_f32_e32 v97, v97
	s_nop 0
	v_add_f32_e32 v97, 1.0, v97
	v_rcp_f32_e32 v99, v97
	s_nop 0
	v_mul_f32_e32 v97, v122, v99
	v_mul_f32_e32 v97, v106, v97
	v_cvt_pk_bf16_f32 v97, v97, s0
	ds_write_b16 v96, v97 offset:2592
	v_mul_f32_e32 v97, 0xbfb8aa3b, v123
	v_exp_f32_e32 v97, v97
	s_nop 0
	v_add_f32_e32 v97, 1.0, v97
	v_rcp_f32_e32 v99, v97
	s_nop 0
	v_mul_f32_e32 v97, v123, v99
	v_mul_f32_e32 v97, v107, v97
	v_cvt_pk_bf16_f32 v97, v97, s0
	ds_write_b16 v96, v97 offset:2736
	v_mul_f32_e32 v97, 0xbfb8aa3b, v124
	v_exp_f32_e32 v97, v97
	s_nop 0
	v_add_f32_e32 v97, 1.0, v97
	v_rcp_f32_e32 v99, v97
	s_nop 0
	v_mul_f32_e32 v97, v124, v99
	v_mul_f32_e32 v97, v108, v97
	v_cvt_pk_bf16_f32 v97, v97, s0
	ds_write_b16 v96, v97 offset:3456
	v_mul_f32_e32 v97, 0xbfb8aa3b, v125
	v_exp_f32_e32 v97, v97
	s_nop 0
	v_add_f32_e32 v97, 1.0, v97
	v_rcp_f32_e32 v99, v97
	s_nop 0
	v_mul_f32_e32 v97, v125, v99
	v_mul_f32_e32 v97, v109, v97
	v_cvt_pk_bf16_f32 v97, v97, s0
	ds_write_b16 v96, v97 offset:3600
	v_mul_f32_e32 v97, 0xbfb8aa3b, v126
	v_exp_f32_e32 v97, v97
	s_nop 0
	v_add_f32_e32 v97, 1.0, v97
	v_rcp_f32_e32 v99, v97
	s_nop 0
	v_mul_f32_e32 v97, v126, v99
	v_mul_f32_e32 v97, v110, v97
	v_cvt_pk_bf16_f32 v97, v97, s0
	ds_write_b16 v96, v97 offset:3744
	v_mul_f32_e32 v97, 0xbfb8aa3b, v127
	v_exp_f32_e32 v97, v97
	s_nop 0
	v_add_f32_e32 v97, 1.0, v97
	v_rcp_f32_e32 v99, v97
	s_nop 0
	v_mul_f32_e32 v97, v127, v99
	v_mul_f32_e32 v97, v111, v97
	v_cvt_pk_bf16_f32 v97, v97, s0
	ds_write_b16 v96, v97 offset:3888
	v_mul_f32_e32 v97, 0xbfb8aa3b, v80
	v_exp_f32_e32 v97, v97
	s_nop 0
	v_add_f32_e32 v97, 1.0, v97
	v_rcp_f32_e32 v99, v97
	s_nop 0
	v_mul_f32_e32 v80, v80, v99
	v_mul_f32_e32 v64, v64, v80
	v_cvt_pk_bf16_f32 v64, v64, s0
	ds_write_b16 v96, v64 offset:4608
	v_mul_f32_e32 v64, 0xbfb8aa3b, v81
	v_exp_f32_e32 v64, v64
	s_nop 0
	v_add_f32_e32 v64, 1.0, v64
	v_rcp_f32_e32 v97, v64
	s_nop 0
	v_mul_f32_e32 v64, v81, v97
	v_mul_f32_e32 v64, v65, v64
	v_cvt_pk_bf16_f32 v64, v64, s0
	ds_write_b16 v96, v64 offset:4752
	v_mul_f32_e32 v64, 0xbfb8aa3b, v82
	v_exp_f32_e32 v64, v64
	s_nop 0
	v_add_f32_e32 v64, 1.0, v64
	v_rcp_f32_e32 v80, v64
	s_nop 0
	v_mul_f32_e32 v64, v82, v80
	v_mul_f32_e32 v64, v66, v64
	v_cvt_pk_bf16_f32 v64, v64, s0
	ds_write_b16 v96, v64 offset:4896
	v_mul_f32_e32 v64, 0xbfb8aa3b, v83
	v_exp_f32_e32 v64, v64
	s_nop 0
	v_add_f32_e32 v64, 1.0, v64
	v_rcp_f32_e32 v66, v64
	s_nop 0
	v_mul_f32_e32 v64, v83, v66
	v_mul_f32_e32 v64, v67, v64
	v_cvt_pk_bf16_f32 v64, v64, s0
	ds_write_b16 v96, v64 offset:5040
	v_mul_f32_e32 v64, 0xbfb8aa3b, v84
	v_exp_f32_e32 v64, v64
	s_nop 0
	v_add_f32_e32 v64, 1.0, v64
	v_rcp_f32_e32 v66, v64
	s_nop 0
	v_mul_f32_e32 v64, v84, v66
	v_mul_f32_e32 v64, v68, v64
	v_cvt_pk_bf16_f32 v64, v64, s0
	ds_write_b16 v96, v64 offset:5760
	v_mul_f32_e32 v64, 0xbfb8aa3b, v85
	v_exp_f32_e32 v64, v64
	s_nop 0
	v_add_f32_e32 v64, 1.0, v64
	v_rcp_f32_e32 v66, v64
	s_nop 0
	v_mul_f32_e32 v64, v85, v66
	v_mul_f32_e32 v64, v69, v64
	v_cvt_pk_bf16_f32 v64, v64, s0
	ds_write_b16 v96, v64 offset:5904
	v_mul_f32_e32 v64, 0xbfb8aa3b, v86
	v_exp_f32_e32 v64, v64
	s_nop 0
	v_add_f32_e32 v64, 1.0, v64
	v_rcp_f32_e32 v66, v64
	s_nop 0
	v_mul_f32_e32 v64, v86, v66
	v_mul_f32_e32 v64, v70, v64
	v_cvt_pk_bf16_f32 v64, v64, s0
	ds_write_b16 v96, v64 offset:6048
	v_mul_f32_e32 v64, 0xbfb8aa3b, v87
	v_exp_f32_e32 v64, v64
	s_nop 0
	v_add_f32_e32 v64, 1.0, v64
	v_rcp_f32_e32 v66, v64
	s_nop 0
	v_mul_f32_e32 v64, v87, v66
	v_mul_f32_e32 v64, v71, v64
	v_cvt_pk_bf16_f32 v64, v64, s0
	ds_write_b16 v96, v64 offset:6192
	v_mul_f32_e32 v64, 0xbfb8aa3b, v88
	v_exp_f32_e32 v64, v64
	v_ashrrev_i32_e32 v71, 5, v130
	v_or_b32_e32 v70, 1, v71
	v_add_f32_e32 v64, 1.0, v64
	v_rcp_f32_e32 v66, v64
	s_nop 0
	v_mul_f32_e32 v64, v88, v66
	v_mul_f32_e32 v64, v72, v64
	v_cvt_pk_bf16_f32 v64, v64, s0
	ds_write_b16 v96, v64 offset:6912
	v_mul_f32_e32 v64, 0xbfb8aa3b, v89
	v_exp_f32_e32 v64, v64
	s_nop 0
	v_add_f32_e32 v64, 1.0, v64
	v_rcp_f32_e32 v66, v64
	s_nop 0
	v_mul_f32_e32 v64, v89, v66
	v_mul_f32_e32 v64, v73, v64
	v_cvt_pk_bf16_f32 v64, v64, s0
	ds_write_b16 v96, v64 offset:7056
	v_mul_f32_e32 v64, 0xbfb8aa3b, v90
	v_exp_f32_e32 v64, v64
	s_nop 0
	v_add_f32_e32 v64, 1.0, v64
	v_rcp_f32_e32 v66, v64
	s_nop 0
	v_mul_f32_e32 v64, v90, v66
	v_mul_f32_e32 v64, v74, v64
	v_cvt_pk_bf16_f32 v64, v64, s0
	ds_write_b16 v96, v64 offset:7200
	v_mul_f32_e32 v64, 0xbfb8aa3b, v91
	v_exp_f32_e32 v64, v64
	s_nop 0
	v_add_f32_e32 v64, 1.0, v64
	v_rcp_f32_e32 v66, v64
	s_nop 0
	v_mul_f32_e32 v64, v91, v66
	v_mul_f32_e32 v64, v75, v64
	v_cvt_pk_bf16_f32 v64, v64, s0
	ds_write_b16 v96, v64 offset:7344
	v_mul_f32_e32 v64, 0xbfb8aa3b, v92
	v_exp_f32_e32 v64, v64
	s_nop 0
	v_add_f32_e32 v64, 1.0, v64
	v_rcp_f32_e32 v66, v64
	s_nop 0
	v_mul_f32_e32 v64, v92, v66
	v_mul_f32_e32 v64, v76, v64
	v_cvt_pk_bf16_f32 v64, v64, s0
	ds_write_b16 v96, v64 offset:8064
	v_mul_f32_e32 v64, 0xbfb8aa3b, v93
	v_exp_f32_e32 v64, v64
	s_nop 0
	v_add_f32_e32 v64, 1.0, v64
	v_rcp_f32_e32 v66, v64
	s_nop 0
	v_mul_f32_e32 v64, v93, v66
	v_mul_f32_e32 v64, v77, v64
	v_cvt_pk_bf16_f32 v64, v64, s0
	ds_write_b16 v96, v64 offset:8208
	v_mul_f32_e32 v64, 0xbfb8aa3b, v94
	v_exp_f32_e32 v64, v64
	s_nop 0
	v_add_f32_e32 v64, 1.0, v64
	v_rcp_f32_e32 v66, v64
	s_nop 0
	v_mul_f32_e32 v64, v94, v66
	v_mul_f32_e32 v64, v78, v64
	v_cvt_pk_bf16_f32 v64, v64, s0
	ds_write_b16 v96, v64 offset:8352
	v_mul_f32_e32 v64, 0xbfb8aa3b, v95
	v_exp_f32_e32 v64, v64
	s_nop 0
	v_add_f32_e32 v64, 1.0, v64
	v_rcp_f32_e32 v66, v64
	s_nop 0
	v_mul_f32_e32 v64, v95, v66
	v_mul_f32_e32 v64, v79, v64
	v_cvt_pk_bf16_f32 v64, v64, s0
	ds_write_b16 v96, v64 offset:8496
	v_ashrrev_i32_e32 v68, 4, v131
	s_waitcnt lgkmcnt(0)
	v_ashrrev_i32_e32 v69, 31, v68
	ds_read_b128 v[72:75], v128
	v_mad_i64_i32 v[64:65], s[0:1], v71, s23, v[68:69]
	v_lshlrev_b64 v[64:65], 10, v[64:65]
	v_lshlrev_b32_e32 v66, 6, v181
	v_lshl_add_u64 v[64:65], s[66:67], 0, v[64:65]
	v_and_b32_e32 v176, 0x200, v66
	v_lshl_add_u64 v[76:77], v[64:65], 0, v[176:177]
	v_lshlrev_b32_e32 v66, 4, v129
	v_mov_b32_e32 v67, v177
	v_lshl_add_u64 v[64:65], v[76:77], 0, v[66:67]
	s_waitcnt lgkmcnt(0)
	global_store_dwordx4 v[64:65], v[72:75], off
	ds_read_b128 v[72:75], v128 offset:2304
	v_or_b32_e32 v64, 0x100, v66
	v_mov_b32_e32 v65, v177
	v_lshl_add_u64 v[76:77], v[76:77], 0, v[64:65]
	s_waitcnt lgkmcnt(0)
	global_store_dwordx4 v[76:77], v[72:75], off
	ds_read_b128 v[72:75], v128 offset:4608
	v_mad_i64_i32 v[76:77], s[0:1], v70, s23, v[68:69]
	v_lshlrev_b64 v[76:77], 10, v[76:77]
	v_lshl_add_u64 v[76:77], s[66:67], 0, v[76:77]
	v_lshl_add_u64 v[76:77], v[76:77], 0, v[176:177]
	v_lshl_add_u64 v[78:79], v[76:77], 0, v[66:67]
	v_mul_f32_e32 v69, 0xbfb8aa3b, v48
	s_waitcnt lgkmcnt(0)
	global_store_dwordx4 v[78:79], v[72:75], off
	ds_read_b128 v[72:75], v128 offset:6912
	v_exp_f32_e32 v69, v69
	v_lshl_add_u64 v[76:77], v[76:77], 0, v[64:65]
	v_add_f32_e32 v69, 1.0, v69
	s_waitcnt lgkmcnt(0)
	global_store_dwordx4 v[76:77], v[72:75], off
	s_waitcnt lgkmcnt(0)
	s_nop 1
	v_rcp_f32_e32 v73, v69
	s_nop 0
	v_mul_f32_e32 v48, v48, v73
	v_mul_f32_e32 v32, v32, v48
	v_cvt_pk_bf16_f32 v32, v32, s0
	ds_write_b16 v96, v32
	v_mul_f32_e32 v32, 0xbfb8aa3b, v49
	v_exp_f32_e32 v32, v32
	s_nop 0
	v_add_f32_e32 v32, 1.0, v32
	v_rcp_f32_e32 v69, v32
	s_nop 0
	v_mul_f32_e32 v32, v49, v69
	v_mul_f32_e32 v32, v33, v32
	v_cvt_pk_bf16_f32 v32, v32, s0
	ds_write_b16 v96, v32 offset:144
	v_mul_f32_e32 v32, 0xbfb8aa3b, v50
	v_exp_f32_e32 v32, v32
	s_nop 0
	v_add_f32_e32 v32, 1.0, v32
	v_rcp_f32_e32 v48, v32
	s_nop 0
	v_mul_f32_e32 v32, v50, v48
	v_mul_f32_e32 v32, v34, v32
	v_cvt_pk_bf16_f32 v32, v32, s0
	ds_write_b16 v96, v32 offset:288
	v_mul_f32_e32 v32, 0xbfb8aa3b, v51
	v_exp_f32_e32 v32, v32
	s_nop 0
	v_add_f32_e32 v32, 1.0, v32
	v_rcp_f32_e32 v34, v32
	s_nop 0
	v_mul_f32_e32 v32, v51, v34
	v_mul_f32_e32 v32, v35, v32
	v_cvt_pk_bf16_f32 v32, v32, s0
	ds_write_b16 v96, v32 offset:432
	v_mul_f32_e32 v32, 0xbfb8aa3b, v52
	v_exp_f32_e32 v32, v32
	s_nop 0
	v_add_f32_e32 v32, 1.0, v32
	v_rcp_f32_e32 v34, v32
	s_nop 0
	v_mul_f32_e32 v32, v52, v34
	v_mul_f32_e32 v32, v36, v32
	v_cvt_pk_bf16_f32 v32, v32, s0
	ds_write_b16 v96, v32 offset:1152
	v_mul_f32_e32 v32, 0xbfb8aa3b, v53
	v_exp_f32_e32 v32, v32
	s_nop 0
	v_add_f32_e32 v32, 1.0, v32
	v_rcp_f32_e32 v34, v32
	s_nop 0
	v_mul_f32_e32 v32, v53, v34
	v_mul_f32_e32 v32, v37, v32
	v_cvt_pk_bf16_f32 v32, v32, s0
	ds_write_b16 v96, v32 offset:1296
	v_mul_f32_e32 v32, 0xbfb8aa3b, v54
	v_exp_f32_e32 v32, v32
	s_nop 0
	v_add_f32_e32 v32, 1.0, v32
	v_rcp_f32_e32 v34, v32
	s_nop 0
	v_mul_f32_e32 v32, v54, v34
	v_mul_f32_e32 v32, v38, v32
	v_cvt_pk_bf16_f32 v32, v32, s0
	ds_write_b16 v96, v32 offset:1440
	v_mul_f32_e32 v32, 0xbfb8aa3b, v55
	v_exp_f32_e32 v32, v32
	s_nop 0
	v_add_f32_e32 v32, 1.0, v32
	v_rcp_f32_e32 v34, v32
	s_nop 0
	v_mul_f32_e32 v32, v55, v34
	v_mul_f32_e32 v32, v39, v32
	v_cvt_pk_bf16_f32 v32, v32, s0
	ds_write_b16 v96, v32 offset:1584
	v_mul_f32_e32 v32, 0xbfb8aa3b, v56
	v_exp_f32_e32 v32, v32
	s_nop 0
	v_add_f32_e32 v32, 1.0, v32
	v_rcp_f32_e32 v34, v32
	s_nop 0
	v_mul_f32_e32 v32, v56, v34
	v_mul_f32_e32 v32, v40, v32
	v_cvt_pk_bf16_f32 v32, v32, s0
	ds_write_b16 v96, v32 offset:2304
	v_mul_f32_e32 v32, 0xbfb8aa3b, v57
	v_exp_f32_e32 v32, v32
	s_nop 0
	v_add_f32_e32 v32, 1.0, v32
	v_rcp_f32_e32 v34, v32
	s_nop 0
	v_mul_f32_e32 v32, v57, v34
	v_mul_f32_e32 v32, v41, v32
	v_cvt_pk_bf16_f32 v32, v32, s0
	ds_write_b16 v96, v32 offset:2448
	v_mul_f32_e32 v32, 0xbfb8aa3b, v58
	v_exp_f32_e32 v32, v32
	s_nop 0
	v_add_f32_e32 v32, 1.0, v32
	v_rcp_f32_e32 v34, v32
	s_nop 0
	v_mul_f32_e32 v32, v58, v34
	v_mul_f32_e32 v32, v42, v32
	v_cvt_pk_bf16_f32 v32, v32, s0
	ds_write_b16 v96, v32 offset:2592
	v_mul_f32_e32 v32, 0xbfb8aa3b, v59
	v_exp_f32_e32 v32, v32
	s_nop 0
	v_add_f32_e32 v32, 1.0, v32
	v_rcp_f32_e32 v34, v32
	s_nop 0
	v_mul_f32_e32 v32, v59, v34
	v_mul_f32_e32 v32, v43, v32
	v_cvt_pk_bf16_f32 v32, v32, s0
	ds_write_b16 v96, v32 offset:2736
	v_mul_f32_e32 v32, 0xbfb8aa3b, v60
	v_exp_f32_e32 v32, v32
	s_nop 0
	v_add_f32_e32 v32, 1.0, v32
	v_rcp_f32_e32 v34, v32
	s_nop 0
	v_mul_f32_e32 v32, v60, v34
	v_mul_f32_e32 v32, v44, v32
	v_cvt_pk_bf16_f32 v32, v32, s0
	ds_write_b16 v96, v32 offset:3456
	v_mul_f32_e32 v32, 0xbfb8aa3b, v61
	v_exp_f32_e32 v32, v32
	s_nop 0
	v_add_f32_e32 v32, 1.0, v32
	v_rcp_f32_e32 v34, v32
	s_nop 0
	v_mul_f32_e32 v32, v61, v34
	v_mul_f32_e32 v32, v45, v32
	v_cvt_pk_bf16_f32 v32, v32, s0
	ds_write_b16 v96, v32 offset:3600
	v_mul_f32_e32 v32, 0xbfb8aa3b, v62
	v_exp_f32_e32 v32, v32
	s_nop 0
	v_add_f32_e32 v32, 1.0, v32
	v_rcp_f32_e32 v34, v32
	s_nop 0
	v_mul_f32_e32 v32, v62, v34
	v_mul_f32_e32 v32, v46, v32
	v_cvt_pk_bf16_f32 v32, v32, s0
	ds_write_b16 v96, v32 offset:3744
	v_mul_f32_e32 v32, 0xbfb8aa3b, v63
	v_exp_f32_e32 v32, v32
	s_nop 0
	v_add_f32_e32 v32, 1.0, v32
	v_rcp_f32_e32 v34, v32
	s_nop 0
	v_mul_f32_e32 v32, v63, v34
	v_mul_f32_e32 v32, v47, v32
	v_cvt_pk_bf16_f32 v32, v32, s0
	ds_write_b16 v96, v32 offset:3888
	v_mul_f32_e32 v32, 0xbfb8aa3b, v16
	v_exp_f32_e32 v32, v32
	s_nop 0
	v_add_f32_e32 v32, 1.0, v32
	v_rcp_f32_e32 v34, v32
	s_nop 0
	v_mul_f32_e32 v16, v16, v34
	v_mul_f32_e32 v0, v0, v16
	v_cvt_pk_bf16_f32 v0, v0, s0
	ds_write_b16 v96, v0 offset:4608
	v_mul_f32_e32 v0, 0xbfb8aa3b, v17
	v_exp_f32_e32 v0, v0
	s_nop 0
	v_add_f32_e32 v0, 1.0, v0
	v_rcp_f32_e32 v32, v0
	s_nop 0
	v_mul_f32_e32 v0, v17, v32
	v_mul_f32_e32 v0, v1, v0
	v_cvt_pk_bf16_f32 v0, v0, s0
	ds_write_b16 v96, v0 offset:4752
	v_mul_f32_e32 v0, 0xbfb8aa3b, v18
	v_exp_f32_e32 v0, v0
	s_nop 0
	v_add_f32_e32 v0, 1.0, v0
	v_rcp_f32_e32 v16, v0
	s_nop 0
	v_mul_f32_e32 v0, v18, v16
	v_mul_f32_e32 v0, v2, v0
	v_cvt_pk_bf16_f32 v0, v0, s0
	ds_write_b16 v96, v0 offset:4896
	v_mul_f32_e32 v0, 0xbfb8aa3b, v19
	v_exp_f32_e32 v0, v0
	s_nop 0
	v_add_f32_e32 v0, 1.0, v0
	v_rcp_f32_e32 v2, v0
	s_nop 0
	v_mul_f32_e32 v0, v19, v2
	v_mul_f32_e32 v0, v3, v0
	v_cvt_pk_bf16_f32 v0, v0, s0
	ds_write_b16 v96, v0 offset:5040
	v_mul_f32_e32 v0, 0xbfb8aa3b, v20
	v_exp_f32_e32 v0, v0
	s_nop 0
	v_add_f32_e32 v0, 1.0, v0
	v_rcp_f32_e32 v2, v0
	s_nop 0
	v_mul_f32_e32 v0, v20, v2
	v_mul_f32_e32 v0, v4, v0
	v_cvt_pk_bf16_f32 v0, v0, s0
	ds_write_b16 v96, v0 offset:5760
	v_mul_f32_e32 v0, 0xbfb8aa3b, v21
	v_exp_f32_e32 v0, v0
	s_nop 0
	v_add_f32_e32 v0, 1.0, v0
	v_rcp_f32_e32 v2, v0
	s_nop 0
	v_mul_f32_e32 v0, v21, v2
	v_mul_f32_e32 v0, v5, v0
	v_cvt_pk_bf16_f32 v0, v0, s0
	ds_write_b16 v96, v0 offset:5904
	v_mul_f32_e32 v0, 0xbfb8aa3b, v22
	v_exp_f32_e32 v0, v0
	s_nop 0
	v_add_f32_e32 v0, 1.0, v0
	v_rcp_f32_e32 v2, v0
	s_nop 0
	v_mul_f32_e32 v0, v22, v2
	v_mul_f32_e32 v0, v6, v0
	v_cvt_pk_bf16_f32 v0, v0, s0
	ds_write_b16 v96, v0 offset:6048
	v_mul_f32_e32 v0, 0xbfb8aa3b, v23
	v_exp_f32_e32 v0, v0
	s_nop 0
	v_add_f32_e32 v0, 1.0, v0
	v_rcp_f32_e32 v2, v0
	s_nop 0
	v_mul_f32_e32 v0, v23, v2
	v_mul_f32_e32 v0, v7, v0
	v_cvt_pk_bf16_f32 v0, v0, s0
	ds_write_b16 v96, v0 offset:6192
	v_mul_f32_e32 v0, 0xbfb8aa3b, v24
	v_exp_f32_e32 v0, v0
	s_nop 0
	v_add_f32_e32 v0, 1.0, v0
	v_rcp_f32_e32 v2, v0
	s_nop 0
	v_mul_f32_e32 v0, v24, v2
	v_mul_f32_e32 v0, v8, v0
	v_cvt_pk_bf16_f32 v0, v0, s0
	ds_write_b16 v96, v0 offset:6912
	v_mul_f32_e32 v0, 0xbfb8aa3b, v25
	v_exp_f32_e32 v0, v0
	s_nop 0
	v_add_f32_e32 v0, 1.0, v0
	v_rcp_f32_e32 v2, v0
	s_nop 0
	v_mul_f32_e32 v0, v25, v2
	v_mul_f32_e32 v0, v9, v0
	v_cvt_pk_bf16_f32 v0, v0, s0
	ds_write_b16 v96, v0 offset:7056
	v_mul_f32_e32 v0, 0xbfb8aa3b, v26
	v_exp_f32_e32 v0, v0
	s_nop 0
	v_add_f32_e32 v0, 1.0, v0
	v_rcp_f32_e32 v2, v0
	s_nop 0
	v_mul_f32_e32 v0, v26, v2
	v_mul_f32_e32 v0, v10, v0
	v_cvt_pk_bf16_f32 v0, v0, s0
	ds_write_b16 v96, v0 offset:7200
	v_mul_f32_e32 v0, 0xbfb8aa3b, v27
	v_exp_f32_e32 v0, v0
	s_nop 0
	v_add_f32_e32 v0, 1.0, v0
	v_rcp_f32_e32 v2, v0
	s_nop 0
	v_mul_f32_e32 v0, v27, v2
	v_mul_f32_e32 v0, v11, v0
	v_cvt_pk_bf16_f32 v0, v0, s0
	ds_write_b16 v96, v0 offset:7344
	v_mul_f32_e32 v0, 0xbfb8aa3b, v28
	v_exp_f32_e32 v0, v0
	s_nop 0
	v_add_f32_e32 v0, 1.0, v0
	v_rcp_f32_e32 v2, v0
	s_nop 0
	v_mul_f32_e32 v0, v28, v2
	v_mul_f32_e32 v0, v12, v0
	v_cvt_pk_bf16_f32 v0, v0, s0
	ds_write_b16 v96, v0 offset:8064
	v_mul_f32_e32 v0, 0xbfb8aa3b, v29
	v_exp_f32_e32 v0, v0
	s_nop 0
	v_add_f32_e32 v0, 1.0, v0
	v_rcp_f32_e32 v2, v0
	s_nop 0
	v_mul_f32_e32 v0, v29, v2
	v_mul_f32_e32 v0, v13, v0
	v_cvt_pk_bf16_f32 v0, v0, s0
	ds_write_b16 v96, v0 offset:8208
	v_mul_f32_e32 v0, 0xbfb8aa3b, v30
	v_exp_f32_e32 v0, v0
	s_nop 0
	v_add_f32_e32 v0, 1.0, v0
	v_rcp_f32_e32 v2, v0
	s_nop 0
	v_mul_f32_e32 v0, v30, v2
	v_mul_f32_e32 v0, v14, v0
	v_cvt_pk_bf16_f32 v0, v0, s0
	ds_write_b16 v96, v0 offset:8352
	v_mul_f32_e32 v0, 0xbfb8aa3b, v31
	v_exp_f32_e32 v0, v0
	s_nop 0
	v_add_f32_e32 v0, 1.0, v0
	v_rcp_f32_e32 v2, v0
	s_nop 0
	v_mul_f32_e32 v0, v31, v2
	v_mul_f32_e32 v0, v15, v0
	v_cvt_pk_bf16_f32 v0, v0, s0
	ds_write_b16 v96, v0 offset:8496
	v_or_b32_e32 v4, 2, v68
	s_waitcnt lgkmcnt(0)
	v_ashrrev_i32_e32 v5, 31, v4
	ds_read_b128 v[0:3], v128
	v_mad_i64_i32 v[6:7], s[0:1], v71, s23, v[4:5]
	v_lshlrev_b64 v[6:7], 10, v[6:7]
	v_lshl_add_u64 v[6:7], s[66:67], 0, v[6:7]
	v_lshl_add_u64 v[6:7], v[6:7], 0, v[176:177]
	v_lshl_add_u64 v[8:9], v[6:7], 0, v[66:67]
	s_waitcnt lgkmcnt(0)
	global_store_dwordx4 v[8:9], v[0:3], off
	ds_read_b128 v[0:3], v128 offset:2304
	v_lshl_add_u64 v[6:7], v[6:7], 0, v[64:65]
	v_mad_i64_i32 v[4:5], s[0:1], v70, s23, v[4:5]
	v_lshlrev_b64 v[4:5], 10, v[4:5]
	s_waitcnt lgkmcnt(0)
	global_store_dwordx4 v[6:7], v[0:3], off
	ds_read_b128 v[0:3], v128 offset:4608
	v_lshl_add_u64 v[4:5], s[66:67], 0, v[4:5]
	v_lshl_add_u64 v[4:5], v[4:5], 0, v[176:177]
	v_lshl_add_u64 v[6:7], v[4:5], 0, v[66:67]
	v_lshl_add_u64 v[4:5], v[4:5], 0, v[64:65]
	s_waitcnt lgkmcnt(0)
	global_store_dwordx4 v[6:7], v[0:3], off
	ds_read_b128 v[0:3], v128 offset:6912
	v_readlane_b32 s0, v254, 11
	s_add_i32 s2, s2, s0
	s_cmp_lt_i32 s2, s3
	s_waitcnt lgkmcnt(0)
	global_store_dwordx4 v[4:5], v[0:3], off
	s_waitcnt lgkmcnt(0)
	s_barrier
	s_cbranch_scc1 .LBB0_1031

.LBB0_1087:
	s_add_i32 s9, s8, 4
	s_min_u32 s10, s9, 0x57
	s_lshl_b32 s96, s10, 13
	v_lshl_add_u64 v[168:169], v[186:187], 0, s[96:97]
	v_add_co_u32_e32 v172, vcc, s85, v168
	s_add_i32 s9, s8, 2
	s_nop 0
	v_addc_co_u32_e32 v173, vcc, 0, v169, vcc
	ds_read_b128 v[196:199], v240
	ds_read_b128 v[200:203], v240 offset:2560
	ds_read_b128 v[204:207], v240 offset:5120
	ds_read_b128 v[242:245], v240 offset:7680
	global_load_dwordx4 v[168:171], v[168:169], off
	s_nop 0
	global_load_dwordx4 v[172:175], v[172:173], off
	s_lshl_b32 s96, s10, 11
	s_waitcnt vmcnt(10) lgkmcnt(3)
	v_mfma_f32_32x32x16_bf16 v[112:127], v[160:163], v[196:199], v[112:127]
	s_min_u32 s8, s9, 0x54
	s_add_i32 s8, s8, 3
	s_waitcnt lgkmcnt(2)
	v_mfma_f32_32x32x16_bf16 v[96:111], v[160:163], v[200:203], v[96:111]
	s_waitcnt vmcnt(7)
	v_mfma_f32_32x32x16_bf16 v[48:63], v[164:167], v[196:199], v[48:63]
	ds_read_b128 v[196:199], v240 offset:5152
	s_waitcnt lgkmcnt(2)
	v_mfma_f32_32x32x16_bf16 v[80:95], v[160:163], v[204:207], v[80:95]
	v_mfma_f32_32x32x16_bf16 v[32:47], v[164:167], v[200:203], v[32:47]
	ds_read_b128 v[200:203], v240 offset:7712
	s_waitcnt lgkmcnt(2)
	v_mfma_f32_32x32x16_bf16 v[64:79], v[160:163], v[242:245], v[64:79]
	ds_read_b128 v[160:163], v240 offset:32
	v_mfma_f32_32x32x16_bf16 v[16:31], v[164:167], v[204:207], v[16:31]
	v_mfma_f32_32x32x16_bf16 v[0:15], v[164:167], v[242:245], v[0:15]
	ds_read_b128 v[164:167], v240 offset:2592
	s_waitcnt vmcnt(3)
	ds_write_b128 v188, v[140:143] offset:10240
	s_waitcnt vmcnt(2)
	ds_write_b128 v188, v[144:147] offset:15360
	v_lshl_add_u64 v[140:141], v[184:185], 0, s[96:97]
	v_add_co_u32_e32 v142, vcc, s24, v140
	s_lshl_b32 s96, s8, 13
	s_nop 0
	v_addc_co_u32_e32 v143, vcc, 0, v141, vcc
	v_lshl_add_u64 v[144:145], v[186:187], 0, s[96:97]
	v_add_co_u32_e32 v146, vcc, s85, v144
	s_waitcnt lgkmcnt(3)
	v_mfma_f32_32x32x16_bf16 v[112:127], v[148:151], v[160:163], v[112:127]
	v_addc_co_u32_e32 v147, vcc, 0, v145, vcc
	s_waitcnt lgkmcnt(2)
	v_mfma_f32_32x32x16_bf16 v[96:111], v[148:151], v[164:167], v[96:111]
	v_mfma_f32_32x32x16_bf16 v[80:95], v[148:151], v[196:199], v[80:95]
	v_mfma_f32_32x32x16_bf16 v[64:79], v[148:151], v[200:203], v[64:79]
	v_mfma_f32_32x32x16_bf16 v[48:63], v[128:131], v[160:163], v[48:63]
	v_mfma_f32_32x32x16_bf16 v[32:47], v[128:131], v[164:167], v[32:47]
	global_load_dwordx4 v[164:167], v[142:143], off
	global_load_dwordx4 v[160:163], v[140:141], off
	global_load_dwordx4 v[148:151], v[140:141], off offset:1024
	v_mfma_f32_32x32x16_bf16 v[16:31], v[128:131], v[196:199], v[16:31]
	v_mfma_f32_32x32x16_bf16 v[0:15], v[128:131], v[200:203], v[0:15]
	global_load_dwordx4 v[128:131], v[142:143], off offset:1024
	s_waitcnt lgkmcnt(0)
	s_barrier
	ds_read_b128 v[196:199], v240 offset:10240
	ds_read_b128 v[200:203], v240 offset:12800
	ds_read_b128 v[204:207], v240 offset:15360
	ds_read_b128 v[242:245], v240 offset:17920
	global_load_dwordx4 v[140:143], v[144:145], off
	s_nop 0
	global_load_dwordx4 v[144:147], v[146:147], off
	s_lshl_b32 s96, s8, 11
	s_waitcnt lgkmcnt(3)
	v_mfma_f32_32x32x16_bf16 v[112:127], v[152:155], v[196:199], v[112:127]
	s_mov_b32 s8, s9
	s_cmpk_lt_u32 s9, 0x56
	s_waitcnt lgkmcnt(2)
	v_mfma_f32_32x32x16_bf16 v[96:111], v[152:155], v[200:203], v[96:111]
	v_mfma_f32_32x32x16_bf16 v[48:63], v[156:159], v[196:199], v[48:63]
	ds_read_b128 v[196:199], v240 offset:15392
	s_waitcnt lgkmcnt(2)
	v_mfma_f32_32x32x16_bf16 v[80:95], v[152:155], v[204:207], v[80:95]
	v_mfma_f32_32x32x16_bf16 v[32:47], v[156:159], v[200:203], v[32:47]
	ds_read_b128 v[200:203], v240 offset:17952
	s_waitcnt lgkmcnt(2)
	v_mfma_f32_32x32x16_bf16 v[64:79], v[152:155], v[242:245], v[64:79]
	ds_read_b128 v[152:155], v240 offset:10272
	v_mfma_f32_32x32x16_bf16 v[16:31], v[156:159], v[204:207], v[16:31]
	v_mfma_f32_32x32x16_bf16 v[0:15], v[156:159], v[242:245], v[0:15]
	ds_read_b128 v[156:159], v240 offset:12832
	s_waitcnt lgkmcnt(1)
	v_mfma_f32_32x32x16_bf16 v[112:127], v[136:139], v[152:155], v[112:127]
	s_waitcnt lgkmcnt(0)
	v_mfma_f32_32x32x16_bf16 v[96:111], v[136:139], v[156:159], v[96:111]
	v_mfma_f32_32x32x16_bf16 v[80:95], v[136:139], v[196:199], v[80:95]
	v_mfma_f32_32x32x16_bf16 v[64:79], v[136:139], v[200:203], v[64:79]
	v_lshl_add_u64 v[136:137], v[184:185], 0, s[96:97]
	v_mfma_f32_32x32x16_bf16 v[16:31], v[132:135], v[196:199], v[16:31]
	v_add_co_u32_e32 v196, vcc, s24, v136
	s_nop 1
	v_addc_co_u32_e32 v197, vcc, 0, v137, vcc
	v_mfma_f32_32x32x16_bf16 v[48:63], v[132:135], v[152:155], v[48:63]
	v_mfma_f32_32x32x16_bf16 v[32:47], v[132:135], v[156:159], v[32:47]
	global_load_dwordx4 v[156:159], v[196:197], off
	global_load_dwordx4 v[152:155], v[136:137], off
	s_nop 0
	global_load_dwordx4 v[136:139], v[136:137], off offset:1024
	v_mfma_f32_32x32x16_bf16 v[0:15], v[132:135], v[200:203], v[0:15]
	global_load_dwordx4 v[132:135], v[196:197], off offset:1024
	s_waitcnt vmcnt(11)
	ds_write_b128 v188, v[168:171]
	s_waitcnt vmcnt(10)
	ds_write_b128 v188, v[172:175] offset:5120
	s_waitcnt lgkmcnt(0)
	s_barrier
	s_cbranch_scc1 .LBB0_1087
	s_movk_i32 s8, 0x2400
	s_waitcnt vmcnt(0)
	v_and_b32_e32 v132, 0xffffffc0, v181
	v_mul_lo_u32 v129, v237, s8
	v_lshlrev_b32_e32 v130, 2, v238
	v_lshl_add_u32 v156, s7, 8, v132
	v_mul_u32_u24_e32 v132, 0x110, v183
	v_or_b32_e32 v131, v129, v130
	v_lshlrev_b32_e32 v132, 2, v132
	v_add_u32_e32 v131, v131, v132
	v_add3_u32 v132, v129, v132, v130
	v_readlane_b32 s8, v253, 36
	v_lshlrev_b32_e32 v128, 2, v181
	v_add_u32_e32 v133, 0x800, v131
	v_add_u32_e32 v134, 0x800, v132
	v_lshrrev_b32_e32 v155, 4, v239
	v_readlane_b32 s12, v253, 40
	v_readlane_b32 s13, v253, 41
	v_readlane_b32 s14, v253, 42
	v_readlane_b32 s15, v253, 43
	v_readlane_b32 s16, v253, 44
	v_readlane_b32 s17, v253, 45
	v_readlane_b32 s18, v253, 46
	v_readlane_b32 s19, v253, 47
	v_and_b32_e32 v128, 60, v128
	ds_write2_b32 v131, v112, v113 offset1:68
	ds_write2_b32 v132, v96, v97 offset0:32 offset1:100
	ds_write2_b32 v131, v114, v115 offset0:136 offset1:204
	ds_write2_b32 v132, v98, v99 offset0:168 offset1:236
	ds_write2_b32 v133, v116, v117 offset0:32 offset1:100
	ds_write2_b32 v134, v100, v101 offset0:64 offset1:132
	ds_write2_b32 v133, v118, v119 offset0:168 offset1:236
	v_or_b32_e32 v100, v156, v155
	v_readlane_b32 s20, v253, 48
	v_readlane_b32 s21, v253, 49
	v_readlane_b32 s22, v253, 50
	v_readlane_b32 s23, v253, 51
	s_mov_b64 s[12:13], s[16:17]
	v_lshl_or_b32 v144, v128, 2, v129
	v_lshl_or_b32 v128, s6, 7, v128
	s_movk_i32 s6, 0x110
	v_cmp_gt_i32_e32 vcc, s39, v100
	v_add_u32_e32 v96, 0xffff8000, v100
	v_ashrrev_i32_e32 v97, 31, v100
	s_mov_b64 s[14:15], s[18:19]
	v_mad_u32_u24 v130, v155, s6, v144
	v_cndmask_b32_e32 v97, 0, v97, vcc
	v_cndmask_b32_e32 v96, v96, v100, vcc
	v_mov_b32_e32 v144, s63
	v_mov_b32_e32 v145, s15
	v_mov_b32_e32 v146, s62
	v_mov_b32_e32 v147, s14
	v_min_i32_e32 v100, 0x8000, v100
	v_add_u32_e32 v135, 0xa00, v132
	v_add_u32_e32 v136, 0x1000, v131
	v_add_u32_e32 v137, 0x1000, v132
	v_add_u32_e32 v138, 0x1200, v131
	v_add_u32_e32 v139, 0x1200, v132
	v_add_u32_e32 v140, 0x1800, v131
	v_add_u32_e32 v141, 0x1800, v132
	v_add_u32_e32 v142, 0x1a00, v131
	v_add_u32_e32 v143, 0x1c00, v132
	v_ashrrev_i32_e32 v129, 31, v128
	v_cndmask_b32_e32 v99, v144, v145, vcc
	v_cndmask_b32_e32 v98, v146, v147, vcc
	v_lshlrev_b64 v[96:97], 12, v[96:97]
	v_ashrrev_i32_e32 v100, 12, v100
	ds_write2_b32 v135, v102, v103 offset0:72 offset1:140
	ds_write2_b32 v136, v120, v121 offset0:64 offset1:132
	ds_write2_b32 v137, v104, v105 offset0:96 offset1:164
	ds_write2_b32 v138, v122, v123 offset0:72 offset1:140
	ds_write2_b32 v139, v106, v107 offset0:104 offset1:172
	ds_write2_b32 v140, v124, v125 offset0:96 offset1:164
	ds_write2_b32 v141, v108, v109 offset0:128 offset1:196
	ds_write2_b32 v142, v126, v127 offset0:104 offset1:172
	ds_write2_b32 v143, v110, v111 offset0:8 offset1:76
	v_lshl_add_u64 v[98:99], v[98:99], 0, v[96:97]
	v_lshlrev_b64 v[96:97], 2, v[128:129]
	v_mul_hi_i32_i24_e32 v101, 0x6000, v100
	v_mul_i32_i24_e32 v100, 0x6000, v100
	s_waitcnt lgkmcnt(0)
	v_lshl_add_u64 v[98:99], v[98:99], 0, v[96:97]
	v_lshl_add_u64 v[100:101], s[0:1], 0, v[100:101]
	v_lshl_add_u64 v[100:101], v[100:101], 0, v[96:97]
	ds_read_b128 v[102:105], v130
	global_load_dwordx4 v[106:109], v[98:99], off
	global_load_dwordx4 v[110:113], v[100:101], off
	v_or_b32_e32 v148, 4, v155
	v_or_b32_e32 v149, 8, v155
	v_or_b32_e32 v150, 12, v155
	v_or_b32_e32 v151, 16, v155
	v_or_b32_e32 v152, 20, v155
	v_or_b32_e32 v153, 24, v155
	v_or_b32_e32 v154, 28, v155
	v_or_b32_e32 v157, v156, v154
	v_readlane_b32 s6, v254, 11
	s_add_i32 s2, s2, s6
	s_cmp_lt_i32 s2, s26
	v_readlane_b32 s9, v253, 37
	v_readlane_b32 s10, v253, 38
	v_readlane_b32 s11, v253, 39
	s_mov_b64 s[16:17], s[20:21]
	s_mov_b64 s[18:19], s[22:23]
	s_waitcnt vmcnt(0) lgkmcnt(0)
	v_pk_fma_f32 v[102:103], v[102:103], v[110:111], v[106:107]
	v_pk_fma_f32 v[104:105], v[104:105], v[112:113], v[108:109]
	v_or_b32_e32 v106, v156, v148
	global_store_dwordx4 v[98:99], v[102:105], off
	v_cmp_gt_i32_e32 vcc, s39, v106
	s_nop 0
	v_ashrrev_i32_e32 v102, 31, v106
	v_add_u32_e32 v104, 0xffff8000, v106
	v_cndmask_b32_e32 v103, 0, v102, vcc
	v_cndmask_b32_e32 v102, v104, v106, vcc
	v_cndmask_b32_e32 v105, v144, v145, vcc
	v_cndmask_b32_e32 v104, v146, v147, vcc
	v_lshlrev_b64 v[102:103], 12, v[102:103]
	v_lshl_add_u64 v[102:103], v[104:105], 0, v[102:103]
	v_min_i32_e32 v104, 0x8000, v106
	v_ashrrev_i32_e32 v104, 12, v104
	v_mul_hi_i32_i24_e32 v105, 0x6000, v104
	v_mul_i32_i24_e32 v104, 0x6000, v104
	v_lshl_add_u64 v[102:103], v[102:103], 0, v[96:97]
	v_lshl_add_u64 v[104:105], s[0:1], 0, v[104:105]
	v_lshl_add_u64 v[104:105], v[104:105], 0, v[96:97]
	ds_read_b128 v[106:109], v130 offset:1088
	global_load_dwordx4 v[110:113], v[102:103], off
	global_load_dwordx4 v[114:117], v[104:105], off
	s_waitcnt vmcnt(0) lgkmcnt(0)
	v_pk_fma_f32 v[106:107], v[106:107], v[114:115], v[110:111]
	v_pk_fma_f32 v[108:109], v[108:109], v[116:117], v[112:113]
	v_or_b32_e32 v110, v156, v149
	global_store_dwordx4 v[102:103], v[106:109], off
	v_cmp_gt_i32_e32 vcc, s39, v110
	s_nop 0
	v_ashrrev_i32_e32 v106, 31, v110
	v_add_u32_e32 v108, 0xffff8000, v110
	v_cndmask_b32_e32 v107, 0, v106, vcc
	v_cndmask_b32_e32 v106, v108, v110, vcc
	v_cndmask_b32_e32 v109, v144, v145, vcc
	v_cndmask_b32_e32 v108, v146, v147, vcc
	v_lshlrev_b64 v[106:107], 12, v[106:107]
	v_lshl_add_u64 v[106:107], v[108:109], 0, v[106:107]
	v_min_i32_e32 v108, 0x8000, v110
	v_ashrrev_i32_e32 v108, 12, v108
	v_mul_hi_i32_i24_e32 v109, 0x6000, v108
	v_mul_i32_i24_e32 v108, 0x6000, v108
	v_lshl_add_u64 v[106:107], v[106:107], 0, v[96:97]
	v_lshl_add_u64 v[108:109], s[0:1], 0, v[108:109]
	v_lshl_add_u64 v[108:109], v[108:109], 0, v[96:97]
	ds_read_b128 v[110:113], v130 offset:2176
	global_load_dwordx4 v[114:117], v[106:107], off
	global_load_dwordx4 v[118:121], v[108:109], off
	s_waitcnt vmcnt(0) lgkmcnt(0)
	v_pk_fma_f32 v[110:111], v[110:111], v[118:119], v[114:115]
	v_pk_fma_f32 v[112:113], v[112:113], v[120:121], v[116:117]
	v_or_b32_e32 v114, v156, v150
	global_store_dwordx4 v[106:107], v[110:113], off
	v_cmp_gt_i32_e32 vcc, s39, v114
	s_nop 0
	v_ashrrev_i32_e32 v110, 31, v114
	v_add_u32_e32 v112, 0xffff8000, v114
	v_cndmask_b32_e32 v111, 0, v110, vcc
	v_cndmask_b32_e32 v110, v112, v114, vcc
	v_cndmask_b32_e32 v113, v144, v145, vcc
	v_cndmask_b32_e32 v112, v146, v147, vcc
	v_lshlrev_b64 v[110:111], 12, v[110:111]
	v_lshl_add_u64 v[110:111], v[112:113], 0, v[110:111]
	v_min_i32_e32 v112, 0x8000, v114
	v_ashrrev_i32_e32 v112, 12, v112
	v_mul_hi_i32_i24_e32 v113, 0x6000, v112
	v_mul_i32_i24_e32 v112, 0x6000, v112
	v_lshl_add_u64 v[110:111], v[110:111], 0, v[96:97]
	v_lshl_add_u64 v[112:113], s[0:1], 0, v[112:113]
	v_lshl_add_u64 v[112:113], v[112:113], 0, v[96:97]
	ds_read_b128 v[114:117], v130 offset:3264
	global_load_dwordx4 v[118:121], v[110:111], off
	global_load_dwordx4 v[122:125], v[112:113], off
	s_waitcnt vmcnt(0) lgkmcnt(0)
	v_pk_fma_f32 v[114:115], v[114:115], v[122:123], v[118:119]
	v_pk_fma_f32 v[116:117], v[116:117], v[124:125], v[120:121]
	v_or_b32_e32 v118, v156, v151
	global_store_dwordx4 v[110:111], v[114:117], off
	v_cmp_gt_i32_e32 vcc, s39, v118
	s_nop 0
	v_ashrrev_i32_e32 v114, 31, v118
	v_add_u32_e32 v116, 0xffff8000, v118
	v_cndmask_b32_e32 v115, 0, v114, vcc
	v_cndmask_b32_e32 v114, v116, v118, vcc
	v_cndmask_b32_e32 v117, v144, v145, vcc
	v_cndmask_b32_e32 v116, v146, v147, vcc
	v_lshlrev_b64 v[114:115], 12, v[114:115]
	v_lshl_add_u64 v[114:115], v[116:117], 0, v[114:115]
	v_min_i32_e32 v116, 0x8000, v118
	v_ashrrev_i32_e32 v116, 12, v116
	v_mul_hi_i32_i24_e32 v117, 0x6000, v116
	v_mul_i32_i24_e32 v116, 0x6000, v116
	v_lshl_add_u64 v[114:115], v[114:115], 0, v[96:97]
	v_lshl_add_u64 v[116:117], s[0:1], 0, v[116:117]
	v_lshl_add_u64 v[116:117], v[116:117], 0, v[96:97]
	ds_read_b128 v[118:121], v130 offset:4352
	global_load_dwordx4 v[122:125], v[114:115], off
	global_load_dwordx4 v[126:129], v[116:117], off
	s_waitcnt vmcnt(0) lgkmcnt(0)
	v_pk_fma_f32 v[118:119], v[118:119], v[126:127], v[122:123]
	v_pk_fma_f32 v[120:121], v[120:121], v[128:129], v[124:125]
	v_or_b32_e32 v122, v156, v152
	global_store_dwordx4 v[114:115], v[118:121], off
	v_cmp_gt_i32_e32 vcc, s39, v122
	s_nop 0
	v_ashrrev_i32_e32 v118, 31, v122
	v_add_u32_e32 v120, 0xffff8000, v122
	v_cndmask_b32_e32 v119, 0, v118, vcc
	v_cndmask_b32_e32 v118, v120, v122, vcc
	v_cndmask_b32_e32 v121, v144, v145, vcc
	v_cndmask_b32_e32 v120, v146, v147, vcc
	v_lshlrev_b64 v[118:119], 12, v[118:119]
	v_lshl_add_u64 v[118:119], v[120:121], 0, v[118:119]
	v_min_i32_e32 v120, 0x8000, v122
	v_ashrrev_i32_e32 v120, 12, v120
	v_mul_hi_i32_i24_e32 v121, 0x6000, v120
	v_mul_i32_i24_e32 v120, 0x6000, v120
	v_lshl_add_u64 v[118:119], v[118:119], 0, v[96:97]
	v_lshl_add_u64 v[120:121], s[0:1], 0, v[120:121]
	v_lshl_add_u64 v[120:121], v[120:121], 0, v[96:97]
	ds_read_b128 v[122:125], v130 offset:5440
	global_load_dwordx4 v[126:129], v[118:119], off
	global_load_dwordx4 v[158:161], v[120:121], off
	s_waitcnt vmcnt(0) lgkmcnt(0)
	v_pk_fma_f32 v[122:123], v[122:123], v[158:159], v[126:127]
	v_pk_fma_f32 v[124:125], v[124:125], v[160:161], v[128:129]
	v_or_b32_e32 v126, v156, v153
	global_store_dwordx4 v[118:119], v[122:125], off
	v_cmp_gt_i32_e32 vcc, s39, v126
	s_nop 0
	v_ashrrev_i32_e32 v122, 31, v126
	v_add_u32_e32 v124, 0xffff8000, v126
	v_cndmask_b32_e32 v123, 0, v122, vcc
	v_cndmask_b32_e32 v122, v124, v126, vcc
	v_cndmask_b32_e32 v125, v144, v145, vcc
	v_cndmask_b32_e32 v124, v146, v147, vcc
	v_lshlrev_b64 v[122:123], 12, v[122:123]
	v_lshl_add_u64 v[122:123], v[124:125], 0, v[122:123]
	v_min_i32_e32 v124, 0x8000, v126
	v_ashrrev_i32_e32 v124, 12, v124
	v_mul_hi_i32_i24_e32 v125, 0x6000, v124
	v_mul_i32_i24_e32 v124, 0x6000, v124
	v_lshl_add_u64 v[122:123], v[122:123], 0, v[96:97]
	v_lshl_add_u64 v[124:125], s[0:1], 0, v[124:125]
	v_lshl_add_u64 v[124:125], v[124:125], 0, v[96:97]
	ds_read_b128 v[126:129], v130 offset:6528
	global_load_dwordx4 v[158:161], v[122:123], off
	global_load_dwordx4 v[162:165], v[124:125], off
	v_cmp_gt_i32_e32 vcc, s39, v157
	s_waitcnt vmcnt(0) lgkmcnt(0)
	v_pk_fma_f32 v[126:127], v[126:127], v[162:163], v[158:159]
	v_pk_fma_f32 v[128:129], v[128:129], v[164:165], v[160:161]
	global_store_dwordx4 v[122:123], v[126:129], off
	ds_read_b128 v[158:161], v130 offset:7616
	s_nop 0
	v_ashrrev_i32_e32 v126, 31, v157
	v_add_u32_e32 v128, 0xffff8000, v157
	v_cndmask_b32_e32 v127, 0, v126, vcc
	v_cndmask_b32_e32 v126, v128, v157, vcc
	v_cndmask_b32_e32 v129, v144, v145, vcc
	v_cndmask_b32_e32 v128, v146, v147, vcc
	v_lshlrev_b64 v[126:127], 12, v[126:127]
	v_lshl_add_u64 v[126:127], v[128:129], 0, v[126:127]
	v_min_i32_e32 v128, 0x8000, v157
	v_ashrrev_i32_e32 v128, 12, v128
	v_mul_hi_i32_i24_e32 v129, 0x6000, v128
	v_mul_i32_i24_e32 v128, 0x6000, v128
	v_lshl_add_u64 v[126:127], v[126:127], 0, v[96:97]
	v_lshl_add_u64 v[128:129], s[0:1], 0, v[128:129]
	v_lshl_add_u64 v[128:129], v[128:129], 0, v[96:97]
	global_load_dwordx4 v[162:165], v[126:127], off
	global_load_dwordx4 v[166:169], v[128:129], off
	s_waitcnt vmcnt(0) lgkmcnt(0)
	v_pk_fma_f32 v[158:159], v[158:159], v[166:167], v[162:163]
	v_pk_fma_f32 v[160:161], v[160:161], v[168:169], v[164:165]
	global_store_dwordx4 v[126:127], v[158:161], off
	s_waitcnt lgkmcnt(0)
	ds_write2_b32 v131, v80, v81 offset1:68
	ds_write2_b32 v132, v64, v65 offset0:32 offset1:100
	ds_write2_b32 v131, v82, v83 offset0:136 offset1:204
	ds_write2_b32 v132, v66, v67 offset0:168 offset1:236
	ds_write2_b32 v133, v84, v85 offset0:32 offset1:100
	ds_write2_b32 v134, v68, v69 offset0:64 offset1:132
	ds_write2_b32 v133, v86, v87 offset0:168 offset1:236
	ds_write2_b32 v135, v70, v71 offset0:72 offset1:140
	ds_write2_b32 v136, v88, v89 offset0:64 offset1:132
	ds_write2_b32 v137, v72, v73 offset0:96 offset1:164
	ds_write2_b32 v138, v90, v91 offset0:72 offset1:140
	ds_write2_b32 v139, v74, v75 offset0:104 offset1:172
	ds_write2_b32 v140, v92, v93 offset0:96 offset1:164
	ds_write2_b32 v141, v76, v77 offset0:128 offset1:196
	ds_write2_b32 v142, v94, v95 offset0:104 offset1:172
	ds_write2_b32 v143, v78, v79 offset0:8 offset1:76
	s_waitcnt lgkmcnt(0)
	ds_read_b128 v[64:67], v130
	global_load_dwordx4 v[68:71], v[98:99], off offset:256
	global_load_dwordx4 v[72:75], v[100:101], off offset:256
	s_waitcnt vmcnt(0) lgkmcnt(0)
	v_pk_fma_f32 v[64:65], v[64:65], v[72:73], v[68:69]
	v_pk_fma_f32 v[66:67], v[66:67], v[74:75], v[70:71]
	global_store_dwordx4 v[98:99], v[64:67], off offset:256
	ds_read_b128 v[64:67], v130 offset:1088
	global_load_dwordx4 v[68:71], v[102:103], off offset:256
	global_load_dwordx4 v[72:75], v[104:105], off offset:256
	s_waitcnt vmcnt(0) lgkmcnt(0)
	v_pk_fma_f32 v[64:65], v[64:65], v[72:73], v[68:69]
	v_pk_fma_f32 v[66:67], v[66:67], v[74:75], v[70:71]
	global_store_dwordx4 v[102:103], v[64:67], off offset:256
	ds_read_b128 v[64:67], v130 offset:2176
	global_load_dwordx4 v[68:71], v[106:107], off offset:256
	global_load_dwordx4 v[72:75], v[108:109], off offset:256
	s_waitcnt vmcnt(0) lgkmcnt(0)
	v_pk_fma_f32 v[64:65], v[64:65], v[72:73], v[68:69]
	v_pk_fma_f32 v[66:67], v[66:67], v[74:75], v[70:71]
	global_store_dwordx4 v[106:107], v[64:67], off offset:256
	ds_read_b128 v[64:67], v130 offset:3264
	global_load_dwordx4 v[68:71], v[110:111], off offset:256
	global_load_dwordx4 v[72:75], v[112:113], off offset:256
	s_waitcnt vmcnt(0) lgkmcnt(0)
	v_pk_fma_f32 v[64:65], v[64:65], v[72:73], v[68:69]
	v_pk_fma_f32 v[66:67], v[66:67], v[74:75], v[70:71]
	global_store_dwordx4 v[110:111], v[64:67], off offset:256
	ds_read_b128 v[64:67], v130 offset:4352
	global_load_dwordx4 v[68:71], v[114:115], off offset:256
	global_load_dwordx4 v[72:75], v[116:117], off offset:256
	s_waitcnt vmcnt(0) lgkmcnt(0)
	v_pk_fma_f32 v[64:65], v[64:65], v[72:73], v[68:69]
	v_pk_fma_f32 v[66:67], v[66:67], v[74:75], v[70:71]
	global_store_dwordx4 v[114:115], v[64:67], off offset:256
	ds_read_b128 v[64:67], v130 offset:5440
	global_load_dwordx4 v[68:71], v[118:119], off offset:256
	global_load_dwordx4 v[72:75], v[120:121], off offset:256
	s_waitcnt vmcnt(0) lgkmcnt(0)
	v_pk_fma_f32 v[64:65], v[64:65], v[72:73], v[68:69]
	v_pk_fma_f32 v[66:67], v[66:67], v[74:75], v[70:71]
	global_store_dwordx4 v[118:119], v[64:67], off offset:256
	ds_read_b128 v[64:67], v130 offset:6528
	global_load_dwordx4 v[68:71], v[122:123], off offset:256
	global_load_dwordx4 v[72:75], v[124:125], off offset:256
	s_waitcnt vmcnt(0) lgkmcnt(0)
	v_pk_fma_f32 v[64:65], v[64:65], v[72:73], v[68:69]
	v_pk_fma_f32 v[66:67], v[66:67], v[74:75], v[70:71]
	global_store_dwordx4 v[122:123], v[64:67], off offset:256
	ds_read_b128 v[64:67], v130 offset:7616
	global_load_dwordx4 v[68:71], v[126:127], off offset:256
	global_load_dwordx4 v[72:75], v[128:129], off offset:256
	s_waitcnt vmcnt(0) lgkmcnt(0)
	v_pk_fma_f32 v[64:65], v[64:65], v[72:73], v[68:69]
	v_pk_fma_f32 v[66:67], v[66:67], v[74:75], v[70:71]
	global_store_dwordx4 v[126:127], v[64:67], off offset:256
	s_waitcnt lgkmcnt(0)
	ds_write2_b32 v131, v48, v49 offset1:68
	ds_write2_b32 v132, v32, v33 offset0:32 offset1:100
	ds_write2_b32 v131, v50, v51 offset0:136 offset1:204
	ds_write2_b32 v132, v34, v35 offset0:168 offset1:236
	ds_write2_b32 v133, v52, v53 offset0:32 offset1:100
	ds_write2_b32 v134, v36, v37 offset0:64 offset1:132
	ds_write2_b32 v133, v54, v55 offset0:168 offset1:236
	ds_write2_b32 v135, v38, v39 offset0:72 offset1:140
	ds_write2_b32 v136, v56, v57 offset0:64 offset1:132
	ds_write2_b32 v137, v40, v41 offset0:96 offset1:164
	ds_write2_b32 v138, v58, v59 offset0:72 offset1:140
	ds_write2_b32 v139, v42, v43 offset0:104 offset1:172
	ds_write2_b32 v140, v60, v61 offset0:96 offset1:164
	ds_write2_b32 v141, v44, v45 offset0:128 offset1:196
	ds_write2_b32 v142, v62, v63 offset0:104 offset1:172
	ds_write2_b32 v143, v46, v47 offset0:8 offset1:76
	v_or_b32_e32 v64, 32, v156
	v_or_b32_e32 v36, v64, v155
	v_cmp_gt_i32_e32 vcc, s39, v36
	v_ashrrev_i32_e32 v32, 31, v36
	v_add_u32_e32 v34, 0xffff8000, v36
	v_cndmask_b32_e32 v33, 0, v32, vcc
	v_cndmask_b32_e32 v32, v34, v36, vcc
	v_cndmask_b32_e32 v35, v144, v145, vcc
	v_cndmask_b32_e32 v34, v146, v147, vcc
	v_lshlrev_b64 v[32:33], 12, v[32:33]
	v_lshl_add_u64 v[32:33], v[34:35], 0, v[32:33]
	v_min_i32_e32 v34, 0x8000, v36
	v_ashrrev_i32_e32 v34, 12, v34
	v_mul_hi_i32_i24_e32 v35, 0x6000, v34
	v_mul_i32_i24_e32 v34, 0x6000, v34
	s_waitcnt lgkmcnt(0)
	v_lshl_add_u64 v[32:33], v[32:33], 0, v[96:97]
	v_lshl_add_u64 v[34:35], s[0:1], 0, v[34:35]
	v_lshl_add_u64 v[34:35], v[34:35], 0, v[96:97]
	ds_read_b128 v[36:39], v130
	global_load_dwordx4 v[40:43], v[32:33], off
	global_load_dwordx4 v[44:47], v[34:35], off
	s_waitcnt vmcnt(0) lgkmcnt(0)
	v_pk_fma_f32 v[36:37], v[36:37], v[44:45], v[40:41]
	v_pk_fma_f32 v[38:39], v[38:39], v[46:47], v[42:43]
	v_or_b32_e32 v40, v64, v148
	global_store_dwordx4 v[32:33], v[36:39], off
	v_cmp_gt_i32_e32 vcc, s39, v40
	s_nop 0
	v_ashrrev_i32_e32 v36, 31, v40
	v_add_u32_e32 v38, 0xffff8000, v40
	v_cndmask_b32_e32 v37, 0, v36, vcc
	v_cndmask_b32_e32 v36, v38, v40, vcc
	v_cndmask_b32_e32 v39, v144, v145, vcc
	v_cndmask_b32_e32 v38, v146, v147, vcc
	v_lshlrev_b64 v[36:37], 12, v[36:37]
	v_lshl_add_u64 v[36:37], v[38:39], 0, v[36:37]
	v_min_i32_e32 v38, 0x8000, v40
	v_ashrrev_i32_e32 v38, 12, v38
	v_mul_hi_i32_i24_e32 v39, 0x6000, v38
	v_mul_i32_i24_e32 v38, 0x6000, v38
	v_lshl_add_u64 v[36:37], v[36:37], 0, v[96:97]
	v_lshl_add_u64 v[38:39], s[0:1], 0, v[38:39]
	v_lshl_add_u64 v[38:39], v[38:39], 0, v[96:97]
	ds_read_b128 v[40:43], v130 offset:1088
	global_load_dwordx4 v[44:47], v[36:37], off
	global_load_dwordx4 v[48:51], v[38:39], off
	s_waitcnt vmcnt(0) lgkmcnt(0)
	v_pk_fma_f32 v[40:41], v[40:41], v[48:49], v[44:45]
	v_pk_fma_f32 v[42:43], v[42:43], v[50:51], v[46:47]
	v_or_b32_e32 v44, v64, v149
	global_store_dwordx4 v[36:37], v[40:43], off
	v_cmp_gt_i32_e32 vcc, s39, v44
	s_nop 0
	v_ashrrev_i32_e32 v40, 31, v44
	v_add_u32_e32 v42, 0xffff8000, v44
	v_cndmask_b32_e32 v41, 0, v40, vcc
	v_cndmask_b32_e32 v40, v42, v44, vcc
	v_cndmask_b32_e32 v43, v144, v145, vcc
	v_cndmask_b32_e32 v42, v146, v147, vcc
	v_lshlrev_b64 v[40:41], 12, v[40:41]
	v_lshl_add_u64 v[40:41], v[42:43], 0, v[40:41]
	v_min_i32_e32 v42, 0x8000, v44
	v_ashrrev_i32_e32 v42, 12, v42
	v_mul_hi_i32_i24_e32 v43, 0x6000, v42
	v_mul_i32_i24_e32 v42, 0x6000, v42
	v_lshl_add_u64 v[40:41], v[40:41], 0, v[96:97]
	v_lshl_add_u64 v[42:43], s[0:1], 0, v[42:43]
	v_lshl_add_u64 v[42:43], v[42:43], 0, v[96:97]
	ds_read_b128 v[44:47], v130 offset:2176
	global_load_dwordx4 v[48:51], v[40:41], off
	global_load_dwordx4 v[52:55], v[42:43], off
	s_waitcnt vmcnt(0) lgkmcnt(0)
	v_pk_fma_f32 v[44:45], v[44:45], v[52:53], v[48:49]
	v_pk_fma_f32 v[46:47], v[46:47], v[54:55], v[50:51]
	v_or_b32_e32 v48, v64, v150
	global_store_dwordx4 v[40:41], v[44:47], off
	v_cmp_gt_i32_e32 vcc, s39, v48
	s_nop 0
	v_ashrrev_i32_e32 v44, 31, v48
	v_add_u32_e32 v46, 0xffff8000, v48
	v_cndmask_b32_e32 v45, 0, v44, vcc
	v_cndmask_b32_e32 v44, v46, v48, vcc
	v_cndmask_b32_e32 v47, v144, v145, vcc
	v_cndmask_b32_e32 v46, v146, v147, vcc
	v_lshlrev_b64 v[44:45], 12, v[44:45]
	v_lshl_add_u64 v[44:45], v[46:47], 0, v[44:45]
	v_min_i32_e32 v46, 0x8000, v48
	v_ashrrev_i32_e32 v46, 12, v46
	v_mul_hi_i32_i24_e32 v47, 0x6000, v46
	v_mul_i32_i24_e32 v46, 0x6000, v46
	v_lshl_add_u64 v[44:45], v[44:45], 0, v[96:97]
	v_lshl_add_u64 v[46:47], s[0:1], 0, v[46:47]
	v_lshl_add_u64 v[46:47], v[46:47], 0, v[96:97]
	ds_read_b128 v[48:51], v130 offset:3264
	global_load_dwordx4 v[52:55], v[44:45], off
	global_load_dwordx4 v[56:59], v[46:47], off
	s_waitcnt vmcnt(0) lgkmcnt(0)
	v_pk_fma_f32 v[48:49], v[48:49], v[56:57], v[52:53]
	v_pk_fma_f32 v[50:51], v[50:51], v[58:59], v[54:55]
	v_or_b32_e32 v52, v64, v151
	global_store_dwordx4 v[44:45], v[48:51], off
	v_cmp_gt_i32_e32 vcc, s39, v52
	s_nop 0
	v_ashrrev_i32_e32 v48, 31, v52
	v_add_u32_e32 v50, 0xffff8000, v52
	v_cndmask_b32_e32 v49, 0, v48, vcc
	v_cndmask_b32_e32 v48, v50, v52, vcc
	v_cndmask_b32_e32 v51, v144, v145, vcc
	v_cndmask_b32_e32 v50, v146, v147, vcc
	v_lshlrev_b64 v[48:49], 12, v[48:49]
	v_lshl_add_u64 v[48:49], v[50:51], 0, v[48:49]
	v_min_i32_e32 v50, 0x8000, v52
	v_ashrrev_i32_e32 v50, 12, v50
	v_mul_hi_i32_i24_e32 v51, 0x6000, v50
	v_mul_i32_i24_e32 v50, 0x6000, v50
	v_lshl_add_u64 v[48:49], v[48:49], 0, v[96:97]
	v_lshl_add_u64 v[50:51], s[0:1], 0, v[50:51]
	v_lshl_add_u64 v[50:51], v[50:51], 0, v[96:97]
	ds_read_b128 v[52:55], v130 offset:4352
	global_load_dwordx4 v[56:59], v[48:49], off
	global_load_dwordx4 v[60:63], v[50:51], off
	s_waitcnt vmcnt(0) lgkmcnt(0)
	v_pk_fma_f32 v[52:53], v[52:53], v[60:61], v[56:57]
	v_pk_fma_f32 v[54:55], v[54:55], v[62:63], v[58:59]
	v_or_b32_e32 v56, v64, v152
	global_store_dwordx4 v[48:49], v[52:55], off
	v_cmp_gt_i32_e32 vcc, s39, v56
	s_nop 0
	v_ashrrev_i32_e32 v52, 31, v56
	v_add_u32_e32 v54, 0xffff8000, v56
	v_cndmask_b32_e32 v53, 0, v52, vcc
	v_cndmask_b32_e32 v52, v54, v56, vcc
	v_cndmask_b32_e32 v55, v144, v145, vcc
	v_cndmask_b32_e32 v54, v146, v147, vcc
	v_lshlrev_b64 v[52:53], 12, v[52:53]
	v_lshl_add_u64 v[52:53], v[54:55], 0, v[52:53]
	v_min_i32_e32 v54, 0x8000, v56
	v_ashrrev_i32_e32 v54, 12, v54
	v_mul_hi_i32_i24_e32 v55, 0x6000, v54
	v_mul_i32_i24_e32 v54, 0x6000, v54
	v_lshl_add_u64 v[52:53], v[52:53], 0, v[96:97]
	v_lshl_add_u64 v[54:55], s[0:1], 0, v[54:55]
	v_lshl_add_u64 v[54:55], v[54:55], 0, v[96:97]
	ds_read_b128 v[56:59], v130 offset:5440
	global_load_dwordx4 v[60:63], v[52:53], off
	global_load_dwordx4 v[66:69], v[54:55], off
	s_waitcnt vmcnt(0) lgkmcnt(0)
	v_pk_fma_f32 v[56:57], v[56:57], v[66:67], v[60:61]
	v_pk_fma_f32 v[58:59], v[58:59], v[68:69], v[62:63]
	v_or_b32_e32 v60, v64, v153
	global_store_dwordx4 v[52:53], v[56:59], off
	v_cmp_gt_i32_e32 vcc, s39, v60
	v_or_b32_e32 v64, v64, v154
	v_ashrrev_i32_e32 v56, 31, v60
	v_add_u32_e32 v58, 0xffff8000, v60
	v_cndmask_b32_e32 v57, 0, v56, vcc
	v_cndmask_b32_e32 v56, v58, v60, vcc
	v_cndmask_b32_e32 v59, v144, v145, vcc
	v_cndmask_b32_e32 v58, v146, v147, vcc
	v_lshlrev_b64 v[56:57], 12, v[56:57]
	v_lshl_add_u64 v[56:57], v[58:59], 0, v[56:57]
	v_min_i32_e32 v58, 0x8000, v60
	v_ashrrev_i32_e32 v58, 12, v58
	v_mul_hi_i32_i24_e32 v59, 0x6000, v58
	v_mul_i32_i24_e32 v58, 0x6000, v58
	v_lshl_add_u64 v[56:57], v[56:57], 0, v[96:97]
	v_lshl_add_u64 v[58:59], s[0:1], 0, v[58:59]
	v_lshl_add_u64 v[58:59], v[58:59], 0, v[96:97]
	ds_read_b128 v[60:63], v130 offset:6528
	global_load_dwordx4 v[66:69], v[56:57], off
	global_load_dwordx4 v[70:73], v[58:59], off
	v_cmp_gt_i32_e32 vcc, s39, v64
	s_waitcnt vmcnt(0) lgkmcnt(0)
	v_pk_fma_f32 v[60:61], v[60:61], v[70:71], v[66:67]
	v_pk_fma_f32 v[62:63], v[62:63], v[72:73], v[68:69]
	global_store_dwordx4 v[56:57], v[60:63], off
	s_nop 1
	v_ashrrev_i32_e32 v60, 31, v64
	v_add_u32_e32 v62, 0xffff8000, v64
	v_cndmask_b32_e32 v61, 0, v60, vcc
	v_cndmask_b32_e32 v60, v62, v64, vcc
	v_cndmask_b32_e32 v63, v144, v145, vcc
	v_cndmask_b32_e32 v62, v146, v147, vcc
	v_lshlrev_b64 v[60:61], 12, v[60:61]
	v_lshl_add_u64 v[60:61], v[62:63], 0, v[60:61]
	v_min_i32_e32 v62, 0x8000, v64
	v_ashrrev_i32_e32 v62, 12, v62
	v_mul_hi_i32_i24_e32 v63, 0x6000, v62
	v_mul_i32_i24_e32 v62, 0x6000, v62
	v_lshl_add_u64 v[60:61], v[60:61], 0, v[96:97]
	v_lshl_add_u64 v[62:63], s[0:1], 0, v[62:63]
	v_lshl_add_u64 v[62:63], v[62:63], 0, v[96:97]
	ds_read_b128 v[64:67], v130 offset:7616
	global_load_dwordx4 v[68:71], v[60:61], off
	global_load_dwordx4 v[72:75], v[62:63], off
	s_waitcnt vmcnt(0) lgkmcnt(0)
	v_pk_fma_f32 v[64:65], v[64:65], v[72:73], v[68:69]
	v_pk_fma_f32 v[66:67], v[66:67], v[74:75], v[70:71]
	global_store_dwordx4 v[60:61], v[64:67], off
	s_waitcnt lgkmcnt(0)
	ds_write2_b32 v131, v16, v17 offset1:68
	ds_write2_b32 v132, v0, v1 offset0:32 offset1:100
	ds_write2_b32 v131, v18, v19 offset0:136 offset1:204
	ds_write2_b32 v132, v2, v3 offset0:168 offset1:236
	ds_write2_b32 v133, v20, v21 offset0:32 offset1:100
	ds_write2_b32 v134, v4, v5 offset0:64 offset1:132
	ds_write2_b32 v133, v22, v23 offset0:168 offset1:236
	ds_write2_b32 v135, v6, v7 offset0:72 offset1:140
	ds_write2_b32 v136, v24, v25 offset0:64 offset1:132
	ds_write2_b32 v137, v8, v9 offset0:96 offset1:164
	ds_write2_b32 v138, v26, v27 offset0:72 offset1:140
	ds_write2_b32 v139, v10, v11 offset0:104 offset1:172
	ds_write2_b32 v140, v28, v29 offset0:96 offset1:164
	ds_write2_b32 v141, v12, v13 offset0:128 offset1:196
	ds_write2_b32 v142, v30, v31 offset0:104 offset1:172
	ds_write2_b32 v143, v14, v15 offset0:8 offset1:76
	s_waitcnt lgkmcnt(0)
	ds_read_b128 v[0:3], v130
	global_load_dwordx4 v[4:7], v[32:33], off offset:256
	global_load_dwordx4 v[8:11], v[34:35], off offset:256
	s_waitcnt vmcnt(0) lgkmcnt(0)
	v_pk_fma_f32 v[0:1], v[0:1], v[8:9], v[4:5]
	v_pk_fma_f32 v[2:3], v[2:3], v[10:11], v[6:7]
	global_store_dwordx4 v[32:33], v[0:3], off offset:256
	ds_read_b128 v[0:3], v130 offset:1088
	global_load_dwordx4 v[4:7], v[36:37], off offset:256
	global_load_dwordx4 v[8:11], v[38:39], off offset:256
	s_waitcnt vmcnt(0) lgkmcnt(0)
	v_pk_fma_f32 v[0:1], v[0:1], v[8:9], v[4:5]
	v_pk_fma_f32 v[2:3], v[2:3], v[10:11], v[6:7]
	global_store_dwordx4 v[36:37], v[0:3], off offset:256
	ds_read_b128 v[0:3], v130 offset:2176
	global_load_dwordx4 v[4:7], v[40:41], off offset:256
	global_load_dwordx4 v[8:11], v[42:43], off offset:256
	s_waitcnt vmcnt(0) lgkmcnt(0)
	v_pk_fma_f32 v[0:1], v[0:1], v[8:9], v[4:5]
	v_pk_fma_f32 v[2:3], v[2:3], v[10:11], v[6:7]
	global_store_dwordx4 v[40:41], v[0:3], off offset:256
	ds_read_b128 v[0:3], v130 offset:3264
	global_load_dwordx4 v[4:7], v[44:45], off offset:256
	global_load_dwordx4 v[8:11], v[46:47], off offset:256
	s_waitcnt vmcnt(0) lgkmcnt(0)
	v_pk_fma_f32 v[0:1], v[0:1], v[8:9], v[4:5]
	v_pk_fma_f32 v[2:3], v[2:3], v[10:11], v[6:7]
	global_store_dwordx4 v[44:45], v[0:3], off offset:256
	ds_read_b128 v[0:3], v130 offset:4352
	global_load_dwordx4 v[4:7], v[48:49], off offset:256
	global_load_dwordx4 v[8:11], v[50:51], off offset:256
	s_waitcnt vmcnt(0) lgkmcnt(0)
	v_pk_fma_f32 v[0:1], v[0:1], v[8:9], v[4:5]
	v_pk_fma_f32 v[2:3], v[2:3], v[10:11], v[6:7]
	global_store_dwordx4 v[48:49], v[0:3], off offset:256
	ds_read_b128 v[0:3], v130 offset:5440
	global_load_dwordx4 v[4:7], v[52:53], off offset:256
	global_load_dwordx4 v[8:11], v[54:55], off offset:256
	s_waitcnt vmcnt(0) lgkmcnt(0)
	v_pk_fma_f32 v[0:1], v[0:1], v[8:9], v[4:5]
	v_pk_fma_f32 v[2:3], v[2:3], v[10:11], v[6:7]
	global_store_dwordx4 v[52:53], v[0:3], off offset:256
	ds_read_b128 v[0:3], v130 offset:6528
	global_load_dwordx4 v[4:7], v[56:57], off offset:256
	global_load_dwordx4 v[8:11], v[58:59], off offset:256
	s_waitcnt vmcnt(0) lgkmcnt(0)
	v_pk_fma_f32 v[0:1], v[0:1], v[8:9], v[4:5]
	v_pk_fma_f32 v[2:3], v[2:3], v[10:11], v[6:7]
	global_store_dwordx4 v[56:57], v[0:3], off offset:256
	ds_read_b128 v[0:3], v130 offset:7616
	global_load_dwordx4 v[4:7], v[60:61], off offset:256
	global_load_dwordx4 v[8:11], v[62:63], off offset:256
	s_waitcnt vmcnt(0) lgkmcnt(0)
	v_pk_fma_f32 v[0:1], v[0:1], v[8:9], v[4:5]
	v_pk_fma_f32 v[2:3], v[2:3], v[10:11], v[6:7]
	global_store_dwordx4 v[60:61], v[0:3], off offset:256
	s_waitcnt lgkmcnt(0)
	s_barrier
	s_cbranch_scc1 .LBB0_1086
